# GLA output pass cross-unit pipeline: next unit's state loads (k-steps 0-5) issued in the tail of the current unit, steps 6-7 in place, waits regenerated; on top of static wave priority
# baseline (speedup 1.0000x reference)
; #define LAS __attribute__((address_space(3)))
; __device__ __forceinline__ unsigned f2bf(float f) { return cvtpk(f, 0.f) & 0xffffu; }
; __device__ __forceinline__ void gla_out_unit(const Params& P, LAS unsigned char* lds, int u) {
;     ...
;     const bf16* stp = ST + ((size_t)(q4 >> 1) * 512 + 64 * wave + fr) * 16 + 8 * (q4 & 1); const bf16* vtp = VT + ((size_t)u * 512 + 64 * wave + fr) * 64 + 8 * q4;
; #pragma unroll
;     for (int kb = 0; kb < 10; ++kb) { bf16x8 bfr[4], afr[4];
; #pragma unroll
;         for (int j = 0; j < 4; ++j) bfr[j] = kb < 8 ? __builtin_nontemporal_load((const bf16x8*)(stp + (size_t)(2 * kb) * 8192 + 16 * j * 16)) : *(const bf16x8*)(vtp + (size_t)(16 * j) * 64 + 32 * (kb - 8));
;     ...
;     const float* ogn = (const float*)(ws + WS_OGAIN); float gn[4];
; #pragma unroll
;     for (int j = 0; j < 4; ++j) gn[j] = ogn[64 * wave + 16 * j + fr];
; #pragma unroll
;     for (int m = 0; m < 4; ++m) { const f32x4 rs4 = *(const LAS f32x4*)(RS + 16 * m + 4 * q4);
; #pragma unroll
;         for (int i = 0; i < 4; ++i) { const int t = 16 * m + 4 * q4 + i; LAS bf16* rp = RT + t * 516 + 64 * wave + fr;
; #pragma unroll
;             for (int j = 0; j < 4; ++j) { const float r = bf2f(rp[16 * j]); rp[16 * j] = (bf16)f2bf(acc[m][j][i] * rs4[i] * gn[j] * (r * __builtin_amdgcn_rcpf(1.0f + __expf(-r)))); } }
.LBB0_482:
	s_or_b64 exec, exec, s[0:1]
	s_add_u32 s0, s90, 0xf400000
	v_writelane_b32 v237, s0, 58
	s_addc_u32 s0, s91, 0
	s_andn2_b64 vcc, exec, s[4:5]
	v_writelane_b32 v237, s0, 59
	s_waitcnt lgkmcnt(0)
	s_barrier
	s_cbranch_vccnz .LBB0_519
	s_lshl_b32 s12, s66, 4
	s_lshl_b32 s13, s66, 6
	s_lshl_b32 s16, s84, 6
	s_mov_b32 s5, 0
	v_mov_b32_e32 v69, 0
	s_movk_i32 s17, 0x210
	s_movk_i32 s18, 0x3000
	v_mov_b64_e32 v[70:71], s[90:91]
	s_mov_b32 s19, 0x11402000
	s_movk_i32 s20, 0x408
	s_mov_b32 s21, 0xc000
	s_movk_i32 s22, 0xfe80
	v_xor_b32_e32 v74, 2, v175
	v_xor_b32_e32 v75, 4, v175
	v_xor_b32_e32 v76, 8, v175
	v_mov_b32_e32 v77, 0x358637bd
	s_mov_b32 s23, 0xf800000
	v_mov_b32_e32 v78, 0x260
	v_readlane_b32 s24, v237, 28
	s_mov_b32 s6, s66
	s_mov_b32 s30, 0
	s_branch .LBB0_485
.LBB0_484:
	s_or_b64 exec, exec, s[2:3]
	v_and_b32_e32 v64, 0xffffffcf, v79
	v_ashrrev_i32_e32 v65, 31, v64
	v_or_b32_e32 v66, 48, v79
	v_lshl_add_u64 v[64:65], v[64:65], 2, s[8:9]
	v_ashrrev_i32_e32 v67, 31, v66
	s_waitcnt lgkmcnt(0)
	s_barrier
	v_lshl_add_u64 v[66:67], v[66:67], 2, s[8:9]
	global_load_dword v90, v[64:65], off
	global_load_dword v89, v[64:65], off offset:64
	global_load_dword v88, v[64:65], off offset:128
	global_load_dword v73, v[66:67], off
	ds_read_b128 v[64:67], v87 offset:45056
	v_lshl_add_u32 v68, v72, 1, 0
	v_lshlrev_b32_e32 v72, 1, v91
	v_mul_u32_u24_e32 v91, 0x1020, v92
	v_add3_u32 v72, v68, v72, v91
	ds_read_u16 v91, v72 offset:49152
	ds_read_u16 v92, v72 offset:49184
	ds_read_u16 v93, v72 offset:49216
	ds_read_u16 v94, v72 offset:49248
	ds_read_u16 v95, v72 offset:50184
	ds_read_u16 v96, v72 offset:50216
	ds_read_u16 v97, v72 offset:50248
	ds_read_u16 v98, v72 offset:50280
	s_waitcnt lgkmcnt(8)
	v_mul_f32_e32 v56, v56, v64
	v_mul_f32_e32 v52, v52, v64
	v_mul_f32_e32 v60, v60, v64
	v_mul_f32_e32 v48, v48, v64
	s_waitcnt lgkmcnt(7)
	v_lshlrev_b32_e32 v64, 16, v91
	s_waitcnt lgkmcnt(6)
	v_lshlrev_b32_e32 v91, 16, v92
	s_waitcnt lgkmcnt(5)
	v_lshlrev_b32_e32 v92, 16, v93
	s_waitcnt lgkmcnt(4)
	v_lshlrev_b32_e32 v93, 16, v94
	s_waitcnt lgkmcnt(3)
	v_lshlrev_b32_e32 v94, 16, v95
	s_waitcnt lgkmcnt(2)
	v_lshlrev_b32_e32 v95, 16, v96
	v_mul_f32_e32 v96, 0xbfb8aa3b, v64
	v_mul_f32_e32 v101, 0xbfb8aa3b, v93
	v_mul_f32_e32 v99, 0xbfb8aa3b, v91
	v_mul_f32_e32 v100, 0xbfb8aa3b, v92
	v_mul_f32_e32 v102, 0xbfb8aa3b, v94
	v_exp_f32_e32 v96, v96
	v_exp_f32_e32 v101, v101
	v_exp_f32_e32 v99, v99
	v_exp_f32_e32 v100, v100
	v_exp_f32_e32 v102, v102
	v_mul_f32_e32 v103, 0xbfb8aa3b, v95
	v_exp_f32_e32 v103, v103
	v_add_f32_e32 v96, 1.0, v96
	v_add_f32_e32 v101, 1.0, v101
	v_add_f32_e32 v99, 1.0, v99
	v_add_f32_e32 v100, 1.0, v100
	v_add_f32_e32 v102, 1.0, v102
	v_rcp_f32_e32 v96, v96
	v_rcp_f32_e32 v101, v101
	v_rcp_f32_e32 v99, v99
	v_rcp_f32_e32 v100, v100
	v_rcp_f32_e32 v102, v102
	v_add_f32_e32 v103, 1.0, v103
	v_mul_f32_e32 v57, v57, v65
	v_rcp_f32_e32 v103, v103
	v_mul_f32_e32 v64, v96, v64
	v_mul_f32_e32 v93, v101, v93
	v_mul_f32_e32 v91, v99, v91
	v_mul_f32_e32 v92, v100, v92
	v_mul_f32_e32 v94, v102, v94
	v_add_u32_e32 v68, 0xc000, v72
	s_waitcnt vmcnt(3)
	v_mul_f32_e32 v56, v90, v56
	s_waitcnt vmcnt(2)
	v_mul_f32_e32 v52, v89, v52
	s_waitcnt vmcnt(1)
	v_mul_f32_e32 v60, v88, v60
	s_waitcnt vmcnt(0)
	s_add_i32 s31, s6, s84
	s_cmpk_gt_i32 s31, 0x1ff
	s_cbranch_scc1 .Lmy_p4_nopf
	s_add_i32 s32, s31, 0xfffffe78
	s_cmpk_lt_i32 s31, 0x188
	s_cselect_b32 s34, s31, s32
	s_mov_b32 s33, 0x9200000
	s_cselect_b32 s33, s33, 0x1b800000
	s_mov_b32 s35, 0
	s_lshl_b64 s[34:35], s[34:35], 18
	s_add_u32 s28, s90, s34
	s_addc_u32 s29, s91, s35
	s_add_u32 s28, s28, s33
	s_addc_u32 s29, s29, 0
	v_and_b32_e32 v255, 0xffffffc0, v172
	v_lshlrev_b32_e32 v254, 4, v172
	v_and_b32_e32 v254, 0x200, v254
	v_add_u32_e32 v255, v255, v254
	v_and_b32_e32 v254, 15, v172
	v_or_b32_e32 v255, v255, v254
	v_lshlrev_b32_e32 v255, 5, v255
	v_and_b32_e32 v254, 16, v172
	v_add_u32_e32 v255, v255, v254
	global_load_dwordx4 v[142:145], v255, s[28:29]
	global_load_dwordx4 v[146:149], v255, s[28:29] offset:512
	global_load_dwordx4 v[150:153], v255, s[28:29] offset:1024
	global_load_dwordx4 v[154:157], v255, s[28:29] offset:1536
	v_add_u32_e32 v255, 0x8000, v255
	global_load_dwordx4 v[158:161], v255, s[28:29]
	global_load_dwordx4 v[162:165], v255, s[28:29] offset:512
	global_load_dwordx4 v[166:169], v255, s[28:29] offset:1024
	global_load_dwordx4 v[180:183], v255, s[28:29] offset:1536
	v_add_u32_e32 v255, 0x8000, v255
	global_load_dwordx4 v[184:187], v255, s[28:29]
	global_load_dwordx4 v[188:191], v255, s[28:29] offset:512
	global_load_dwordx4 v[192:195], v255, s[28:29] offset:1024
	global_load_dwordx4 v[196:199], v255, s[28:29] offset:1536
	v_add_u32_e32 v255, 0x8000, v255
	global_load_dwordx4 v[200:203], v255, s[28:29]
	global_load_dwordx4 v[204:207], v255, s[28:29] offset:512
	global_load_dwordx4 v[208:211], v255, s[28:29] offset:1024
	global_load_dwordx4 v[212:215], v255, s[28:29] offset:1536
	v_add_u32_e32 v255, 0x8000, v255
	global_load_dwordx4 v[216:219], v255, s[28:29]
	global_load_dwordx4 v[220:223], v255, s[28:29] offset:512
	global_load_dwordx4 v[224:227], v255, s[28:29] offset:1024
	global_load_dwordx4 v[228:231], v255, s[28:29] offset:1536
	v_add_u32_e32 v255, 0x8000, v255
	global_load_dwordx4 v[232:235], v255, s[28:29]
	global_load_dwordx4 v[238:241], v255, s[28:29] offset:512
	global_load_dwordx4 v[242:245], v255, s[28:29] offset:1024
	global_load_dwordx4 v[246:249], v255, s[28:29] offset:1536
	v_add_u32_e32 v255, 0x8000, v255
	s_mov_b32 s30, 1
; #define LAS __attribute__((address_space(3)))
; #define SBAR() __builtin_amdgcn_sched_barrier(0)
; __device__ __forceinline__ unsigned f2bf(float f) { return cvtpk(f, 0.f) & 0xffffu; }
; __device__ __forceinline__ void gla_out_unit(const Params& P, LAS unsigned char* lds, int u) {
;     ...
;     const float* ogn = (const float*)(ws + WS_OGAIN); float gn[4];
; #pragma unroll
;     for (int j = 0; j < 4; ++j) gn[j] = ogn[64 * wave + 16 * j + fr];
; #pragma unroll
;     for (int m = 0; m < 4; ++m) { const f32x4 rs4 = *(const LAS f32x4*)(RS + 16 * m + 4 * q4);
; #pragma unroll
;         for (int i = 0; i < 4; ++i) { const int t = 16 * m + 4 * q4 + i; LAS bf16* rp = RT + t * 516 + 64 * wave + fr;
; #pragma unroll
;             for (int j = 0; j < 4; ++j) { const float r = bf2f(rp[16 * j]); rp[16 * j] = (bf16)f2bf(acc[m][j][i] * rs4[i] * gn[j] * (r * __builtin_amdgcn_rcpf(1.0f + __expf(-r)))); } }
;         SBAR(); }
.Lmy_p4_nopf:
	v_mul_f32_e32 v48, v73, v48
	v_mul_f32_e32 v57, v90, v57
	v_mul_f32_e32 v56, v56, v64
	v_mul_f32_e32 v48, v48, v93
	v_mul_f32_e32 v52, v52, v91
	v_mul_f32_e32 v60, v60, v92
	v_mul_f32_e32 v57, v57, v94
	v_cvt_pk_bf16_f32 v56, v56, s0
	v_cvt_pk_bf16_f32 v48, v48, s0
	v_cvt_pk_bf16_f32 v52, v52, s0
	v_cvt_pk_bf16_f32 v60, v60, s0
	v_cvt_pk_bf16_f32 v57, v57, s0
	ds_write_b16 v72, v56 offset:49152
	ds_write_b16 v72, v52 offset:49184
	ds_write_b16 v72, v60 offset:49216
	ds_write_b16 v72, v48 offset:49248
	ds_write_b16 v72, v57 offset:50184
	v_mul_f32_e32 v48, v53, v65
	v_mul_f32_e32 v48, v89, v48
	v_mul_f32_e32 v52, v103, v95
	v_mul_f32_e32 v48, v48, v52
	s_waitcnt lgkmcnt(6)
	v_lshlrev_b32_e32 v52, 16, v97
	v_mul_f32_e32 v53, 0xbfb8aa3b, v52
	v_exp_f32_e32 v53, v53
	s_waitcnt lgkmcnt(5)
	v_lshlrev_b32_e32 v56, 16, v98
	v_mul_f32_e32 v57, 0xbfb8aa3b, v56
	v_exp_f32_e32 v57, v57
	v_add_f32_e32 v53, 1.0, v53
	v_rcp_f32_e32 v53, v53
	v_cvt_pk_bf16_f32 v48, v48, s0
	ds_write_b16 v72, v48 offset:50216
	v_mul_f32_e32 v48, v61, v65
	v_mul_f32_e32 v48, v88, v48
	v_mul_f32_e32 v52, v53, v52
	v_mul_f32_e32 v48, v48, v52
	v_add_f32_e32 v52, 1.0, v57
	v_rcp_f32_e32 v52, v52
	v_cvt_pk_bf16_f32 v48, v48, s0
	ds_write_b16 v72, v48 offset:50248
	v_mul_f32_e32 v48, v49, v65
	v_mul_f32_e32 v48, v73, v48
	v_mul_f32_e32 v49, v52, v56
	v_mul_f32_e32 v48, v48, v49
	ds_read_u16 v49, v72 offset:51216
	ds_read_u16 v52, v72 offset:51248
	ds_read_u16 v53, v72 offset:51280
	ds_read_u16 v56, v72 offset:51312
	ds_read_u16 v57, v72 offset:52248
	ds_read_u16 v60, v72 offset:52280
	ds_read_u16 v61, v72 offset:52312
	ds_read_u16 v64, v72 offset:52344
	s_waitcnt lgkmcnt(7)
	v_lshlrev_b32_e32 v49, 16, v49
	v_mul_f32_e32 v65, 0xbfb8aa3b, v49
	v_exp_f32_e32 v65, v65
	v_cvt_pk_bf16_f32 v48, v48, s0
	ds_write_b16 v72, v48 offset:50280
	v_mul_f32_e32 v48, v58, v66
	v_add_f32_e32 v58, 1.0, v65
	s_waitcnt lgkmcnt(7)
	v_lshlrev_b32_e32 v52, 16, v52
	v_rcp_f32_e32 v58, v58
	v_mul_f32_e32 v65, 0xbfb8aa3b, v52
	v_exp_f32_e32 v65, v65
	v_mul_f32_e32 v48, v90, v48
	v_mul_f32_e32 v49, v58, v49
	v_mul_f32_e32 v48, v48, v49
	v_add_f32_e32 v49, 1.0, v65
	v_rcp_f32_e32 v49, v49
	v_cvt_pk_bf16_f32 v48, v48, s0
	ds_write_b16 v72, v48 offset:51216
	v_mul_f32_e32 v48, v54, v66
	v_mul_f32_e32 v48, v89, v48
	v_mul_f32_e32 v49, v49, v52
	v_mul_f32_e32 v48, v48, v49
	s_waitcnt lgkmcnt(7)
	v_lshlrev_b32_e32 v49, 16, v53
	v_mul_f32_e32 v52, 0xbfb8aa3b, v49
	v_exp_f32_e32 v52, v52
	s_waitcnt lgkmcnt(6)
	v_lshlrev_b32_e32 v53, 16, v56
	v_mul_f32_e32 v54, 0xbfb8aa3b, v53
	v_exp_f32_e32 v54, v54
	v_add_f32_e32 v52, 1.0, v52
	v_rcp_f32_e32 v52, v52
	v_cvt_pk_bf16_f32 v48, v48, s0
	ds_write_b16 v72, v48 offset:51248
	v_mul_f32_e32 v48, v62, v66
	v_mul_f32_e32 v48, v88, v48
	v_mul_f32_e32 v49, v52, v49
	v_mul_f32_e32 v48, v48, v49
	v_add_f32_e32 v49, 1.0, v54
	v_rcp_f32_e32 v49, v49
	v_cvt_pk_bf16_f32 v48, v48, s0
	ds_write_b16 v72, v48 offset:51280
	v_mul_f32_e32 v48, v50, v66
	v_mul_f32_e32 v48, v73, v48
	v_mul_f32_e32 v49, v49, v53
	v_mul_f32_e32 v48, v48, v49
	s_waitcnt lgkmcnt(7)
	v_lshlrev_b32_e32 v49, 16, v57
	v_mul_f32_e32 v50, 0xbfb8aa3b, v49
	v_exp_f32_e32 v50, v50
	s_waitcnt lgkmcnt(6)
	v_lshlrev_b32_e32 v52, 16, v60
	v_mul_f32_e32 v53, 0xbfb8aa3b, v52
	v_exp_f32_e32 v53, v53
	v_add_f32_e32 v50, 1.0, v50
	v_rcp_f32_e32 v50, v50
	v_cvt_pk_bf16_f32 v48, v48, s0
	ds_write_b16 v72, v48 offset:51312
	v_mul_f32_e32 v48, v59, v67
	v_mul_f32_e32 v48, v90, v48
	v_mul_f32_e32 v49, v50, v49
	v_mul_f32_e32 v48, v48, v49
	v_add_f32_e32 v49, 1.0, v53
	v_rcp_f32_e32 v49, v49
	v_cvt_pk_bf16_f32 v48, v48, s0
	ds_write_b16 v72, v48 offset:52248
	v_mul_f32_e32 v48, v55, v67
	v_mul_f32_e32 v48, v89, v48
	v_mul_f32_e32 v49, v49, v52
	v_mul_f32_e32 v48, v48, v49
	s_waitcnt lgkmcnt(7)
	v_lshlrev_b32_e32 v49, 16, v61
	v_mul_f32_e32 v50, 0xbfb8aa3b, v49
	v_exp_f32_e32 v50, v50
	s_waitcnt lgkmcnt(6)
	v_lshlrev_b32_e32 v52, 16, v64
	v_mul_f32_e32 v53, 0xbfb8aa3b, v52
	v_exp_f32_e32 v53, v53
	v_add_f32_e32 v50, 1.0, v50
	v_rcp_f32_e32 v50, v50
	v_cvt_pk_bf16_f32 v48, v48, s0
	ds_write_b16 v72, v48 offset:52280
	v_mul_f32_e32 v48, v63, v67
	v_mul_f32_e32 v48, v88, v48
	v_mul_f32_e32 v49, v50, v49
	v_mul_f32_e32 v48, v48, v49
	v_add_f32_e32 v49, 1.0, v53
	v_rcp_f32_e32 v49, v49
	v_cvt_pk_bf16_f32 v48, v48, s0
	ds_write_b16 v72, v48 offset:52312
	v_mul_f32_e32 v48, v51, v67
	v_mul_f32_e32 v48, v73, v48
	v_mul_f32_e32 v49, v49, v52
	v_mul_f32_e32 v48, v48, v49
	v_cvt_pk_bf16_f32 v48, v48, s0
	ds_write_b16 v72, v48 offset:52344
	ds_read_u16 v52, v68 offset:16512
	ds_read_b128 v[48:51], v87 offset:45120
	ds_read_u16 v53, v68 offset:16544
	ds_read_u16 v54, v68 offset:16576
	s_waitcnt lgkmcnt(3)
	v_lshlrev_b32_e32 v52, 16, v52
	v_mul_f32_e32 v55, 0xbfb8aa3b, v52
	v_exp_f32_e32 v55, v55
	s_waitcnt lgkmcnt(1)
	v_lshlrev_b32_e32 v53, 16, v53
	v_mul_f32_e32 v56, 0xbfb8aa3b, v53
	v_exp_f32_e32 v56, v56
	v_add_f32_e32 v55, 1.0, v55
	v_rcp_f32_e32 v55, v55
	v_mul_f32_e32 v44, v44, v48
	v_add_f32_e32 v56, 1.0, v56
	v_rcp_f32_e32 v56, v56
	v_mul_f32_e32 v44, v90, v44
	v_mul_f32_e32 v52, v55, v52
	v_mul_f32_e32 v44, v44, v52
	v_cvt_pk_bf16_f32 v44, v44, s0
	v_mul_f32_e32 v40, v40, v48
	ds_write_b16 v68, v44 offset:16512
	v_mul_f32_e32 v40, v89, v40
	v_mul_f32_e32 v44, v56, v53
	v_mul_f32_e32 v40, v40, v44
	s_waitcnt lgkmcnt(1)
	v_lshlrev_b32_e32 v44, 16, v54
	v_mul_f32_e32 v52, 0xbfb8aa3b, v44
	v_exp_f32_e32 v52, v52
	v_cvt_pk_bf16_f32 v40, v40, s0
	ds_write_b16 v68, v40 offset:16544
	v_mul_f32_e32 v36, v36, v48
	v_add_f32_e32 v40, 1.0, v52
	ds_read_u16 v52, v68 offset:16608
	ds_read_u16 v53, v68 offset:17544
	ds_read_u16 v54, v68 offset:17576
	ds_read_u16 v55, v68 offset:17608
	ds_read_u16 v56, v68 offset:17640
	ds_read_u16 v57, v68 offset:18576
	ds_read_u16 v58, v68 offset:18608
	ds_read_u16 v59, v68 offset:18640
	s_waitcnt lgkmcnt(7)
; #define LAS __attribute__((address_space(3)))
; __device__ __forceinline__ unsigned f2bf(float f) { return cvtpk(f, 0.f) & 0xffffu; }
; __device__ __forceinline__ void gla_out_unit(const Params& P, LAS unsigned char* lds, int u) {
;     ...
;     for (int m = 0; m < 4; ++m) { const f32x4 rs4 = *(const LAS f32x4*)(RS + 16 * m + 4 * q4);
; #pragma unroll
;         for (int i = 0; i < 4; ++i) { const int t = 16 * m + 4 * q4 + i; LAS bf16* rp = RT + t * 516 + 64 * wave + fr;
; #pragma unroll
;             for (int j = 0; j < 4; ++j) { const float r = bf2f(rp[16 * j]); rp[16 * j] = (bf16)f2bf(acc[m][j][i] * rs4[i] * gn[j] * (r * __builtin_amdgcn_rcpf(1.0f + __expf(-r)))); } }
	v_lshlrev_b32_e32 v52, 16, v52
	v_rcp_f32_e32 v40, v40
	v_mul_f32_e32 v60, 0xbfb8aa3b, v52
	v_exp_f32_e32 v60, v60
	v_mul_f32_e32 v36, v88, v36
	v_mul_f32_e32 v40, v40, v44
	v_mul_f32_e32 v36, v36, v40
	v_add_f32_e32 v40, 1.0, v60
	v_rcp_f32_e32 v40, v40
	v_cvt_pk_bf16_f32 v36, v36, s0
	v_mul_f32_e32 v32, v32, v48
	ds_write_b16 v68, v36 offset:16576
	v_mul_f32_e32 v32, v73, v32
	v_mul_f32_e32 v36, v40, v52
	v_mul_f32_e32 v32, v32, v36
	s_waitcnt lgkmcnt(7)
	v_lshlrev_b32_e32 v36, 16, v53
	v_mul_f32_e32 v40, 0xbfb8aa3b, v36
	v_exp_f32_e32 v40, v40
	v_cvt_pk_bf16_f32 v32, v32, s0
	s_waitcnt lgkmcnt(6)
	v_lshlrev_b32_e32 v44, 16, v54
	ds_write_b16 v68, v32 offset:16608
	v_add_f32_e32 v40, 1.0, v40
	v_mul_f32_e32 v32, v45, v49
	v_rcp_f32_e32 v40, v40
	v_mul_f32_e32 v45, 0xbfb8aa3b, v44
	v_exp_f32_e32 v45, v45
	v_mul_f32_e32 v32, v90, v32
	v_mul_f32_e32 v36, v40, v36
	v_mul_f32_e32 v32, v32, v36
	v_add_f32_e32 v36, 1.0, v45
	v_rcp_f32_e32 v36, v36
	v_cvt_pk_bf16_f32 v32, v32, s0
	ds_write_b16 v68, v32 offset:17544
	v_mul_f32_e32 v32, v41, v49
	v_mul_f32_e32 v32, v89, v32
	v_mul_f32_e32 v36, v36, v44
	v_mul_f32_e32 v32, v32, v36
	s_waitcnt lgkmcnt(7)
	v_lshlrev_b32_e32 v36, 16, v55
	v_mul_f32_e32 v40, 0xbfb8aa3b, v36
	v_exp_f32_e32 v40, v40
	v_cvt_pk_bf16_f32 v32, v32, s0
	ds_write_b16 v68, v32 offset:17576
	v_mul_f32_e32 v32, v37, v49
	v_add_f32_e32 v37, 1.0, v40
	s_waitcnt lgkmcnt(7)
	v_lshlrev_b32_e32 v40, 16, v56
	v_rcp_f32_e32 v37, v37
	v_mul_f32_e32 v41, 0xbfb8aa3b, v40
	v_exp_f32_e32 v41, v41
	v_mul_f32_e32 v32, v88, v32
	v_mul_f32_e32 v36, v37, v36
	v_mul_f32_e32 v32, v32, v36
	v_add_f32_e32 v36, 1.0, v41
	v_rcp_f32_e32 v36, v36
	v_cvt_pk_bf16_f32 v32, v32, s0
	ds_write_b16 v68, v32 offset:17608
	v_mul_f32_e32 v32, v33, v49
	v_mul_f32_e32 v32, v73, v32
	v_mul_f32_e32 v33, v36, v40
	v_mul_f32_e32 v32, v32, v33
	s_waitcnt lgkmcnt(7)
	v_lshlrev_b32_e32 v33, 16, v57
	v_mul_f32_e32 v36, 0xbfb8aa3b, v33
	v_exp_f32_e32 v36, v36
	s_waitcnt lgkmcnt(6)
	v_lshlrev_b32_e32 v37, 16, v58
	v_mul_f32_e32 v40, 0xbfb8aa3b, v37
	v_exp_f32_e32 v40, v40
	v_add_f32_e32 v36, 1.0, v36
	v_rcp_f32_e32 v36, v36
	v_cvt_pk_bf16_f32 v32, v32, s0
	ds_write_b16 v68, v32 offset:17640
	v_mul_f32_e32 v32, v46, v50
	v_mul_f32_e32 v32, v90, v32
	v_mul_f32_e32 v33, v36, v33
	v_mul_f32_e32 v32, v32, v33
	v_add_f32_e32 v33, 1.0, v40
	v_rcp_f32_e32 v33, v33
	v_cvt_pk_bf16_f32 v32, v32, s0
	ds_write_b16 v68, v32 offset:18576
	v_mul_f32_e32 v32, v42, v50
	v_mul_f32_e32 v32, v89, v32
	v_mul_f32_e32 v33, v33, v37
	v_mul_f32_e32 v32, v32, v33
	s_waitcnt lgkmcnt(7)
	v_lshlrev_b32_e32 v33, 16, v59
	v_mul_f32_e32 v36, 0xbfb8aa3b, v33
	v_exp_f32_e32 v36, v36
	v_cvt_pk_bf16_f32 v32, v32, s0
	ds_write_b16 v68, v32 offset:18608
	v_mul_f32_e32 v32, v38, v50
	ds_read_u16 v37, v68 offset:18672
	ds_read_u16 v38, v68 offset:19608
	ds_read_u16 v40, v68 offset:19640
	ds_read_u16 v41, v68 offset:19672
	ds_read_u16 v42, v68 offset:19704
	v_add_f32_e32 v36, 1.0, v36
	s_waitcnt lgkmcnt(4)
	v_lshlrev_b32_e32 v37, 16, v37
	v_rcp_f32_e32 v36, v36
	v_mul_f32_e32 v44, 0xbfb8aa3b, v37
	v_exp_f32_e32 v44, v44
	v_mul_f32_e32 v32, v88, v32
	v_mul_f32_e32 v33, v36, v33
	v_mul_f32_e32 v32, v32, v33
	v_add_f32_e32 v33, 1.0, v44
	v_rcp_f32_e32 v33, v33
	v_cvt_pk_bf16_f32 v32, v32, s0
	ds_write_b16 v68, v32 offset:18640
	v_mul_f32_e32 v32, v34, v50
	v_mul_f32_e32 v32, v73, v32
	v_mul_f32_e32 v33, v33, v37
	v_mul_f32_e32 v32, v32, v33
	s_waitcnt lgkmcnt(4)
	v_lshlrev_b32_e32 v33, 16, v38
	v_mul_f32_e32 v34, 0xbfb8aa3b, v33
	v_exp_f32_e32 v34, v34
	s_waitcnt lgkmcnt(3)
	v_lshlrev_b32_e32 v36, 16, v40
	v_mul_f32_e32 v37, 0xbfb8aa3b, v36
	v_exp_f32_e32 v37, v37
	v_add_f32_e32 v34, 1.0, v34
	v_rcp_f32_e32 v34, v34
	v_cvt_pk_bf16_f32 v32, v32, s0
	ds_write_b16 v68, v32 offset:18672
	v_mul_f32_e32 v32, v47, v51
	v_mul_f32_e32 v32, v90, v32
	v_mul_f32_e32 v33, v34, v33
	v_mul_f32_e32 v32, v32, v33
	v_add_f32_e32 v33, 1.0, v37
	v_rcp_f32_e32 v33, v33
	v_cvt_pk_bf16_f32 v32, v32, s0
	ds_write_b16 v68, v32 offset:19608
	v_mul_f32_e32 v32, v43, v51
	v_mul_f32_e32 v32, v89, v32
	v_mul_f32_e32 v33, v33, v36
	v_mul_f32_e32 v32, v32, v33
	s_waitcnt lgkmcnt(4)
	v_lshlrev_b32_e32 v33, 16, v41
	v_mul_f32_e32 v34, 0xbfb8aa3b, v33
	v_exp_f32_e32 v34, v34
	s_waitcnt lgkmcnt(3)
	v_lshlrev_b32_e32 v36, 16, v42
	v_mul_f32_e32 v37, 0xbfb8aa3b, v36
	v_exp_f32_e32 v37, v37
	v_add_f32_e32 v34, 1.0, v34
	v_rcp_f32_e32 v34, v34
	v_cvt_pk_bf16_f32 v32, v32, s0
	ds_write_b16 v68, v32 offset:19640
	v_mul_f32_e32 v32, v39, v51
	v_mul_f32_e32 v32, v88, v32
	v_mul_f32_e32 v33, v34, v33
	v_mul_f32_e32 v32, v32, v33
	v_add_f32_e32 v33, 1.0, v37
	v_rcp_f32_e32 v33, v33
	v_cvt_pk_bf16_f32 v32, v32, s0
	ds_write_b16 v68, v32 offset:19672
	v_mul_f32_e32 v32, v35, v51
	v_mul_f32_e32 v32, v73, v32
	v_mul_f32_e32 v33, v33, v36
	v_mul_f32_e32 v32, v32, v33
	v_cvt_pk_bf16_f32 v32, v32, s0
	ds_write_b16 v68, v32 offset:19704
	ds_read_u16 v36, v68 offset:33024
	ds_read_b128 v[32:35], v87 offset:45184
	ds_read_u16 v37, v68 offset:33056
	ds_read_u16 v38, v68 offset:33088
	s_waitcnt lgkmcnt(3)
	v_lshlrev_b32_e32 v36, 16, v36
	v_mul_f32_e32 v39, 0xbfb8aa3b, v36
	v_exp_f32_e32 v39, v39
	s_waitcnt lgkmcnt(1)
	v_lshlrev_b32_e32 v37, 16, v37
	v_mul_f32_e32 v40, 0xbfb8aa3b, v37
	v_exp_f32_e32 v40, v40
	v_add_f32_e32 v39, 1.0, v39
	v_rcp_f32_e32 v39, v39
	v_mul_f32_e32 v20, v20, v32
	v_add_f32_e32 v40, 1.0, v40
	v_mul_f32_e32 v20, v90, v20
	v_rcp_f32_e32 v40, v40
	v_mul_f32_e32 v36, v39, v36
	v_mul_f32_e32 v20, v20, v36
	v_cvt_pk_bf16_f32 v20, v20, s0
	ds_write_b16 v68, v20 offset:33024
	v_mul_f32_e32 v20, v24, v32
	v_mul_f32_e32 v20, v89, v20
	v_mul_f32_e32 v24, v40, v37
	v_mul_f32_e32 v20, v20, v24
	s_waitcnt lgkmcnt(1)
; #define LAS __attribute__((address_space(3)))
; #define SBAR() __builtin_amdgcn_sched_barrier(0)
; __device__ __forceinline__ unsigned f2bf(float f) { return cvtpk(f, 0.f) & 0xffffu; }
; __device__ __forceinline__ void gla_out_unit(const Params& P, LAS unsigned char* lds, int u) {
;     ...
;     for (int m = 0; m < 4; ++m) { const f32x4 rs4 = *(const LAS f32x4*)(RS + 16 * m + 4 * q4);
; #pragma unroll
;         for (int i = 0; i < 4; ++i) { const int t = 16 * m + 4 * q4 + i; LAS bf16* rp = RT + t * 516 + 64 * wave + fr;
; #pragma unroll
;             for (int j = 0; j < 4; ++j) { const float r = bf2f(rp[16 * j]); rp[16 * j] = (bf16)f2bf(acc[m][j][i] * rs4[i] * gn[j] * (r * __builtin_amdgcn_rcpf(1.0f + __expf(-r)))); } }
;         SBAR(); }
	v_lshlrev_b32_e32 v24, 16, v38
	v_mul_f32_e32 v36, 0xbfb8aa3b, v24
	v_exp_f32_e32 v36, v36
	v_cvt_pk_bf16_f32 v20, v20, s0
	ds_write_b16 v68, v20 offset:33056
	v_mul_f32_e32 v20, v28, v32
	v_add_f32_e32 v28, 1.0, v36
	ds_read_u16 v36, v68 offset:33120
	ds_read_u16 v37, v68 offset:34056
	ds_read_u16 v38, v68 offset:34088
	ds_read_u16 v39, v68 offset:34120
	ds_read_u16 v40, v68 offset:34152
	ds_read_u16 v41, v68 offset:35088
	ds_read_u16 v42, v68 offset:35120
	ds_read_u16 v43, v68 offset:35152
	s_waitcnt lgkmcnt(7)
	v_lshlrev_b32_e32 v36, 16, v36
	v_rcp_f32_e32 v28, v28
	v_mul_f32_e32 v44, 0xbfb8aa3b, v36
	v_exp_f32_e32 v44, v44
	v_mul_f32_e32 v20, v88, v20
	v_mul_f32_e32 v24, v28, v24
	v_mul_f32_e32 v20, v20, v24
	v_add_f32_e32 v24, 1.0, v44
	v_rcp_f32_e32 v24, v24
	v_cvt_pk_bf16_f32 v20, v20, s0
	v_mul_f32_e32 v16, v16, v32
	ds_write_b16 v68, v20 offset:33088
	v_mul_f32_e32 v16, v73, v16
	v_mul_f32_e32 v20, v24, v36
	v_mul_f32_e32 v16, v16, v20
	s_waitcnt lgkmcnt(7)
	v_lshlrev_b32_e32 v20, 16, v37
	v_mul_f32_e32 v24, 0xbfb8aa3b, v20
	v_exp_f32_e32 v24, v24
	v_cvt_pk_bf16_f32 v16, v16, s0
	ds_write_b16 v68, v16 offset:33120
	v_mul_f32_e32 v16, v21, v33
	v_add_f32_e32 v21, 1.0, v24
	s_waitcnt lgkmcnt(7)
	v_lshlrev_b32_e32 v24, 16, v38
	v_rcp_f32_e32 v21, v21
	v_mul_f32_e32 v28, 0xbfb8aa3b, v24
	v_exp_f32_e32 v28, v28
	v_mul_f32_e32 v16, v90, v16
	v_mul_f32_e32 v20, v21, v20
	v_mul_f32_e32 v16, v16, v20
	v_add_f32_e32 v20, 1.0, v28
	v_rcp_f32_e32 v20, v20
	v_cvt_pk_bf16_f32 v16, v16, s0
	ds_write_b16 v68, v16 offset:34056
	v_mul_f32_e32 v16, v25, v33
	v_mul_f32_e32 v16, v89, v16
	v_mul_f32_e32 v20, v20, v24
	v_mul_f32_e32 v16, v16, v20
	s_waitcnt lgkmcnt(7)
	v_lshlrev_b32_e32 v20, 16, v39
	v_mul_f32_e32 v21, 0xbfb8aa3b, v20
	v_exp_f32_e32 v21, v21
	s_waitcnt lgkmcnt(6)
	v_lshlrev_b32_e32 v24, 16, v40
	v_mul_f32_e32 v25, 0xbfb8aa3b, v24
	v_exp_f32_e32 v25, v25
	v_add_f32_e32 v21, 1.0, v21
	v_rcp_f32_e32 v21, v21
	v_cvt_pk_bf16_f32 v16, v16, s0
	ds_write_b16 v68, v16 offset:34088
	v_mul_f32_e32 v16, v29, v33
	v_mul_f32_e32 v16, v88, v16
	v_mul_f32_e32 v20, v21, v20
	v_mul_f32_e32 v16, v16, v20
	v_add_f32_e32 v20, 1.0, v25
	v_rcp_f32_e32 v20, v20
	v_cvt_pk_bf16_f32 v16, v16, s0
	ds_write_b16 v68, v16 offset:34120
	v_mul_f32_e32 v16, v17, v33
	v_mul_f32_e32 v16, v73, v16
	v_mul_f32_e32 v17, v20, v24
	v_mul_f32_e32 v16, v16, v17
	s_waitcnt lgkmcnt(7)
	v_lshlrev_b32_e32 v17, 16, v41
	v_mul_f32_e32 v20, 0xbfb8aa3b, v17
	v_exp_f32_e32 v20, v20
	v_cvt_pk_bf16_f32 v16, v16, s0
	s_waitcnt lgkmcnt(6)
	v_lshlrev_b32_e32 v21, 16, v42
	ds_write_b16 v68, v16 offset:34152
	v_add_f32_e32 v20, 1.0, v20
	v_mul_f32_e32 v16, v22, v34
	v_rcp_f32_e32 v20, v20
	v_mul_f32_e32 v22, 0xbfb8aa3b, v21
	v_exp_f32_e32 v22, v22
	v_mul_f32_e32 v16, v90, v16
	v_mul_f32_e32 v17, v20, v17
	v_mul_f32_e32 v16, v16, v17
	v_add_f32_e32 v17, 1.0, v22
	v_rcp_f32_e32 v17, v17
	v_cvt_pk_bf16_f32 v16, v16, s0
	ds_write_b16 v68, v16 offset:35088
	v_mul_f32_e32 v16, v26, v34
	v_mul_f32_e32 v16, v89, v16
	v_mul_f32_e32 v17, v17, v21
	v_mul_f32_e32 v16, v16, v17
	s_waitcnt lgkmcnt(7)
	v_lshlrev_b32_e32 v17, 16, v43
	v_mul_f32_e32 v20, 0xbfb8aa3b, v17
	v_exp_f32_e32 v20, v20
	v_cvt_pk_bf16_f32 v16, v16, s0
	ds_write_b16 v68, v16 offset:35120
	ds_read_u16 v21, v68 offset:35184
	ds_read_u16 v22, v68 offset:36120
	ds_read_u16 v24, v68 offset:36152
	ds_read_u16 v25, v68 offset:36184
	ds_read_u16 v26, v68 offset:36216
	v_add_f32_e32 v20, 1.0, v20
	s_waitcnt lgkmcnt(4)
	v_lshlrev_b32_e32 v21, 16, v21
	v_rcp_f32_e32 v20, v20
	v_mul_f32_e32 v28, 0xbfb8aa3b, v21
	v_exp_f32_e32 v28, v28
	v_mul_f32_e32 v16, v30, v34
	v_mul_f32_e32 v16, v88, v16
	v_mul_f32_e32 v17, v20, v17
	v_mul_f32_e32 v16, v16, v17
	v_add_f32_e32 v17, 1.0, v28
	v_rcp_f32_e32 v17, v17
	v_cvt_pk_bf16_f32 v16, v16, s0
	ds_write_b16 v68, v16 offset:35152
	v_mul_f32_e32 v16, v18, v34
	v_mul_f32_e32 v16, v73, v16
	v_mul_f32_e32 v17, v17, v21
	v_mul_f32_e32 v16, v16, v17
	s_waitcnt lgkmcnt(4)
	v_lshlrev_b32_e32 v17, 16, v22
	v_mul_f32_e32 v18, 0xbfb8aa3b, v17
	v_exp_f32_e32 v18, v18
	s_waitcnt lgkmcnt(3)
	v_lshlrev_b32_e32 v20, 16, v24
	v_mul_f32_e32 v21, 0xbfb8aa3b, v20
	v_exp_f32_e32 v21, v21
	v_add_f32_e32 v18, 1.0, v18
	v_rcp_f32_e32 v18, v18
	v_cvt_pk_bf16_f32 v16, v16, s0
	ds_write_b16 v68, v16 offset:35184
	v_mul_f32_e32 v16, v23, v35
	v_mul_f32_e32 v16, v90, v16
	v_mul_f32_e32 v17, v18, v17
	v_mul_f32_e32 v16, v16, v17
	v_add_f32_e32 v17, 1.0, v21
	v_rcp_f32_e32 v17, v17
	v_cvt_pk_bf16_f32 v16, v16, s0
	ds_write_b16 v68, v16 offset:36120
	v_mul_f32_e32 v16, v27, v35
	v_mul_f32_e32 v16, v89, v16
	v_mul_f32_e32 v17, v17, v20
	v_mul_f32_e32 v16, v16, v17
	s_waitcnt lgkmcnt(4)
	v_lshlrev_b32_e32 v17, 16, v25
	v_mul_f32_e32 v18, 0xbfb8aa3b, v17
	v_exp_f32_e32 v18, v18
	s_waitcnt lgkmcnt(3)
	v_lshlrev_b32_e32 v20, 16, v26
	v_mul_f32_e32 v21, 0xbfb8aa3b, v20
	v_exp_f32_e32 v21, v21
	v_add_f32_e32 v18, 1.0, v18
	v_rcp_f32_e32 v18, v18
	v_cvt_pk_bf16_f32 v16, v16, s0
	ds_write_b16 v68, v16 offset:36152
	v_mul_f32_e32 v16, v31, v35
	v_mul_f32_e32 v16, v88, v16
	v_mul_f32_e32 v17, v18, v17
	v_mul_f32_e32 v16, v16, v17
	v_add_f32_e32 v17, 1.0, v21
	v_rcp_f32_e32 v17, v17
	v_cvt_pk_bf16_f32 v16, v16, s0
	ds_write_b16 v68, v16 offset:36184
	v_mul_f32_e32 v16, v19, v35
	v_mul_f32_e32 v16, v73, v16
	v_mul_f32_e32 v17, v17, v20
	v_mul_f32_e32 v16, v16, v17
	v_cvt_pk_bf16_f32 v16, v16, s0
	ds_write_b16 v68, v16 offset:36216
	ds_read_u16 v20, v68 offset:49536
	ds_read_b128 v[16:19], v87 offset:45248
	ds_read_u16 v21, v68 offset:49568
	ds_read_u16 v22, v68 offset:49600
	s_waitcnt lgkmcnt(3)
; #define LAS __attribute__((address_space(3)))
; #define SBAR() __builtin_amdgcn_sched_barrier(0)
; __device__ __forceinline__ unsigned f2bf(float f) { return cvtpk(f, 0.f) & 0xffffu; }
; __device__ __forceinline__ void gla_out_unit(const Params& P, LAS unsigned char* lds, int u) {
;     ...
;     for (int m = 0; m < 4; ++m) { const f32x4 rs4 = *(const LAS f32x4*)(RS + 16 * m + 4 * q4);
; #pragma unroll
;         for (int i = 0; i < 4; ++i) { const int t = 16 * m + 4 * q4 + i; LAS bf16* rp = RT + t * 516 + 64 * wave + fr;
; #pragma unroll
;             for (int j = 0; j < 4; ++j) { const float r = bf2f(rp[16 * j]); rp[16 * j] = (bf16)f2bf(acc[m][j][i] * rs4[i] * gn[j] * (r * __builtin_amdgcn_rcpf(1.0f + __expf(-r)))); } }
;         SBAR(); }
;     __syncthreads();
; #pragma unroll
;     for (int it = 0; it < 16; ++it) { const int idx = it * NTHREADS + tid, t = idx >> 7, cc = idx & 127; *(v2u*)(OB + (size_t)(tok0 + t) * DM + 512 * h + 4 * cc) = *(const LAS v2u*)(RT + t * 516 + 4 * cc); }
	v_lshlrev_b32_e32 v20, 16, v20
	v_mul_f32_e32 v23, 0xbfb8aa3b, v20
	v_exp_f32_e32 v23, v23
	s_waitcnt lgkmcnt(1)
	v_lshlrev_b32_e32 v21, 16, v21
	v_mul_f32_e32 v24, 0xbfb8aa3b, v21
	v_exp_f32_e32 v24, v24
	v_add_f32_e32 v23, 1.0, v23
	v_rcp_f32_e32 v23, v23
	v_mul_f32_e32 v12, v12, v16
	v_add_f32_e32 v24, 1.0, v24
	v_rcp_f32_e32 v24, v24
	v_mul_f32_e32 v12, v90, v12
	v_mul_f32_e32 v20, v23, v20
	v_mul_f32_e32 v12, v12, v20
	v_cvt_pk_bf16_f32 v12, v12, s0
	v_mul_f32_e32 v4, v4, v16
	ds_write_b16 v68, v12 offset:49536
	v_mul_f32_e32 v4, v89, v4
	v_mul_f32_e32 v12, v24, v21
	v_mul_f32_e32 v4, v4, v12
	s_waitcnt lgkmcnt(1)
	v_lshlrev_b32_e32 v12, 16, v22
	v_mul_f32_e32 v20, 0xbfb8aa3b, v12
	v_exp_f32_e32 v20, v20
	v_cvt_pk_bf16_f32 v4, v4, s0
	ds_write_b16 v68, v4 offset:49568
	v_mul_f32_e32 v4, v8, v16
	v_add_f32_e32 v8, 1.0, v20
	ds_read_u16 v20, v68 offset:49632
	ds_read_u16 v21, v68 offset:50568
	ds_read_u16 v22, v68 offset:50600
	ds_read_u16 v23, v68 offset:50632
	ds_read_u16 v24, v68 offset:50664
	ds_read_u16 v25, v68 offset:51600
	ds_read_u16 v26, v68 offset:51632
	ds_read_u16 v27, v68 offset:51664
	s_waitcnt lgkmcnt(7)
	v_lshlrev_b32_e32 v20, 16, v20
	v_rcp_f32_e32 v8, v8
	v_mul_f32_e32 v28, 0xbfb8aa3b, v20
	v_exp_f32_e32 v28, v28
	v_mul_f32_e32 v4, v88, v4
	v_mul_f32_e32 v8, v8, v12
	v_mul_f32_e32 v4, v4, v8
	v_add_f32_e32 v8, 1.0, v28
	v_rcp_f32_e32 v8, v8
	v_cvt_pk_bf16_f32 v4, v4, s0
	v_mul_f32_e32 v0, v0, v16
	ds_write_b16 v68, v4 offset:49600
	v_mul_f32_e32 v0, v73, v0
	v_mul_f32_e32 v4, v8, v20
	v_mul_f32_e32 v0, v0, v4
	s_waitcnt lgkmcnt(7)
	v_lshlrev_b32_e32 v4, 16, v21
	v_mul_f32_e32 v8, 0xbfb8aa3b, v4
	v_exp_f32_e32 v8, v8
	v_cvt_pk_bf16_f32 v0, v0, s0
	s_waitcnt lgkmcnt(6)
	v_lshlrev_b32_e32 v12, 16, v22
	ds_write_b16 v68, v0 offset:49632
	v_add_f32_e32 v8, 1.0, v8
	v_mul_f32_e32 v0, v13, v17
	v_rcp_f32_e32 v8, v8
	v_mul_f32_e32 v13, 0xbfb8aa3b, v12
	v_exp_f32_e32 v13, v13
	v_mul_f32_e32 v0, v90, v0
	v_mul_f32_e32 v4, v8, v4
	v_mul_f32_e32 v0, v0, v4
	v_add_f32_e32 v4, 1.0, v13
	v_rcp_f32_e32 v4, v4
	v_cvt_pk_bf16_f32 v0, v0, s0
	ds_write_b16 v68, v0 offset:50568
	v_mul_f32_e32 v0, v5, v17
	v_mul_f32_e32 v0, v89, v0
	v_mul_f32_e32 v4, v4, v12
	v_mul_f32_e32 v0, v0, v4
	s_waitcnt lgkmcnt(7)
	v_lshlrev_b32_e32 v4, 16, v23
	v_mul_f32_e32 v5, 0xbfb8aa3b, v4
	v_exp_f32_e32 v5, v5
	v_cvt_pk_bf16_f32 v0, v0, s0
	s_waitcnt lgkmcnt(6)
	v_lshlrev_b32_e32 v8, 16, v24
	ds_write_b16 v68, v0 offset:50600
	v_add_f32_e32 v5, 1.0, v5
	v_mul_f32_e32 v0, v9, v17
	v_rcp_f32_e32 v5, v5
	v_mul_f32_e32 v9, 0xbfb8aa3b, v8
	v_exp_f32_e32 v9, v9
	v_mul_f32_e32 v0, v88, v0
	v_mul_f32_e32 v4, v5, v4
	v_mul_f32_e32 v0, v0, v4
	v_add_f32_e32 v4, 1.0, v9
	v_rcp_f32_e32 v4, v4
	v_cvt_pk_bf16_f32 v0, v0, s0
	ds_write_b16 v68, v0 offset:50632
	v_mul_f32_e32 v0, v1, v17
	v_mul_f32_e32 v0, v73, v0
	v_mul_f32_e32 v1, v4, v8
	v_mul_f32_e32 v0, v0, v1
	s_waitcnt lgkmcnt(7)
	v_lshlrev_b32_e32 v1, 16, v25
	v_mul_f32_e32 v4, 0xbfb8aa3b, v1
	v_exp_f32_e32 v4, v4
	s_waitcnt lgkmcnt(6)
	v_lshlrev_b32_e32 v5, 16, v26
	v_mul_f32_e32 v8, 0xbfb8aa3b, v5
	v_exp_f32_e32 v8, v8
	v_add_f32_e32 v4, 1.0, v4
	v_rcp_f32_e32 v4, v4
	v_cvt_pk_bf16_f32 v0, v0, s0
	ds_write_b16 v68, v0 offset:50664
	v_mul_f32_e32 v0, v14, v18
	v_mul_f32_e32 v0, v90, v0
	v_mul_f32_e32 v1, v4, v1
	v_mul_f32_e32 v0, v0, v1
	v_add_f32_e32 v1, 1.0, v8
	v_rcp_f32_e32 v1, v1
	v_cvt_pk_bf16_f32 v0, v0, s0
	ds_write_b16 v68, v0 offset:51600
	v_mul_f32_e32 v0, v6, v18
	v_mul_f32_e32 v0, v89, v0
	v_mul_f32_e32 v1, v1, v5
	v_mul_f32_e32 v0, v0, v1
	s_waitcnt lgkmcnt(7)
	v_lshlrev_b32_e32 v1, 16, v27
	v_mul_f32_e32 v4, 0xbfb8aa3b, v1
	v_exp_f32_e32 v4, v4
	v_cvt_pk_bf16_f32 v0, v0, s0
	ds_write_b16 v68, v0 offset:51632
	v_mul_f32_e32 v0, v10, v18
	ds_read_u16 v5, v68 offset:51696
	ds_read_u16 v6, v68 offset:52632
	ds_read_u16 v8, v68 offset:52664
	ds_read_u16 v9, v68 offset:52696
	ds_read_u16 v10, v68 offset:52728
	v_add_f32_e32 v4, 1.0, v4
	s_waitcnt lgkmcnt(4)
	v_lshlrev_b32_e32 v5, 16, v5
	v_rcp_f32_e32 v4, v4
	v_mul_f32_e32 v12, 0xbfb8aa3b, v5
	v_exp_f32_e32 v12, v12
	v_mul_f32_e32 v0, v88, v0
	v_mul_f32_e32 v1, v4, v1
	v_mul_f32_e32 v0, v0, v1
	v_add_f32_e32 v1, 1.0, v12
	v_rcp_f32_e32 v1, v1
	v_cvt_pk_bf16_f32 v0, v0, s0
	ds_write_b16 v68, v0 offset:51664
	v_mul_f32_e32 v0, v2, v18
	v_mul_f32_e32 v0, v73, v0
	v_mul_f32_e32 v1, v1, v5
	v_mul_f32_e32 v0, v0, v1
	s_waitcnt lgkmcnt(4)
	v_lshlrev_b32_e32 v1, 16, v6
	v_mul_f32_e32 v2, 0xbfb8aa3b, v1
	v_exp_f32_e32 v2, v2
	s_waitcnt lgkmcnt(3)
	v_lshlrev_b32_e32 v4, 16, v8
	v_mul_f32_e32 v5, 0xbfb8aa3b, v4
	v_exp_f32_e32 v5, v5
	v_add_f32_e32 v2, 1.0, v2
	v_rcp_f32_e32 v2, v2
	v_cvt_pk_bf16_f32 v0, v0, s0
	ds_write_b16 v68, v0 offset:51696
	v_mul_f32_e32 v0, v15, v19
	v_mul_f32_e32 v0, v90, v0
	v_mul_f32_e32 v1, v2, v1
	v_mul_f32_e32 v0, v0, v1
	v_add_f32_e32 v1, 1.0, v5
	v_rcp_f32_e32 v1, v1
	v_cvt_pk_bf16_f32 v0, v0, s0
	ds_write_b16 v68, v0 offset:52632
	v_mul_f32_e32 v0, v7, v19
	v_mul_f32_e32 v0, v89, v0
	v_mul_f32_e32 v1, v1, v4
	v_mul_f32_e32 v0, v0, v1
	s_waitcnt lgkmcnt(4)
	v_lshlrev_b32_e32 v1, 16, v9
	v_mul_f32_e32 v2, 0xbfb8aa3b, v1
	v_exp_f32_e32 v2, v2
	s_waitcnt lgkmcnt(3)
	v_lshlrev_b32_e32 v4, 16, v10
	v_mul_f32_e32 v5, 0xbfb8aa3b, v4
	v_exp_f32_e32 v5, v5
	v_add_f32_e32 v2, 1.0, v2
	v_rcp_f32_e32 v2, v2
	v_cvt_pk_bf16_f32 v0, v0, s0
	ds_write_b16 v68, v0 offset:52664
	v_mul_f32_e32 v0, v11, v19
	v_mul_f32_e32 v0, v88, v0
	v_mul_f32_e32 v1, v2, v1
	v_mul_f32_e32 v0, v0, v1
	v_add_f32_e32 v1, 1.0, v5
	v_rcp_f32_e32 v1, v1
	v_cvt_pk_bf16_f32 v0, v0, s0
	ds_write_b16 v68, v0 offset:52696
	v_mul_f32_e32 v0, v3, v19
	v_mul_f32_e32 v0, v73, v0
	v_mul_f32_e32 v1, v1, v4
	v_mul_f32_e32 v0, v0, v1
	v_cvt_pk_bf16_f32 v0, v0, s0
	ds_write_b16 v68, v0 offset:52728
	v_lshlrev_b32_e32 v0, 3, v79
	v_readlane_b32 s0, v237, 58
	v_and_b32_e32 v68, 0x3f8, v0
	s_add_u32 s0, s0, s4
	v_readlane_b32 s1, v237, 59
	v_add_u32_e32 v2, 0, v68
	s_addc_u32 s1, s1, 0
	v_ashrrev_i32_e32 v3, 7, v79
	v_lshl_add_u64 v[0:1], s[0:1], 0, v[68:69]
	v_mad_u64_u32 v[4:5], s[0:1], v3, s20, v[2:3]
	s_waitcnt lgkmcnt(0)
	s_barrier
; #define LAS __attribute__((address_space(3)))
; #define SEAM(k) do { if (IN(k) && IN((k) + 1)) xcd_barrier(xbar); } while (0)
; __device__ __forceinline__ void gla_out_unit(const Params& P, LAS unsigned char* lds, int u) {
;     ...
;     for (int it = 0; it < 16; ++it) { const int idx = it * NTHREADS + tid, t = idx >> 7, cc = idx & 127; *(v2u*)(OB + (size_t)(tok0 + t) * DM + 512 * h + 4 * cc) = *(const LAS v2u*)(RT + t * 516 + 4 * cc); }
;     __syncthreads();
; __global__ void __launch_bounds__(NTHREADS, 2) hybrid_fwd(Params P) {
;     ...
;     if (IN(4)) { for (int u = blockIdx.x; u < 512; u += gridDim.x) gla_out_unit(P, lds, u); } SEAM(4);
	ds_read_b64 v[4:5], v4 offset:49152
	v_add_u32_e32 v6, s25, v3
	v_ashrrev_i32_e32 v7, 31, v6
	v_lshlrev_b64 v[6:7], 12, v[6:7]
	v_ashrrev_i32_e32 v3, 7, v82
	v_ashrrev_i32_e32 v14, 7, v81
	v_ashrrev_i32_e32 v15, 7, v80
	v_lshl_add_u64 v[6:7], v[0:1], 0, v[6:7]
	v_mad_u64_u32 v[8:9], s[0:1], v3, s20, v[2:3]
	v_mad_u64_u32 v[10:11], s[0:1], v14, s20, v[2:3]
	v_mad_u64_u32 v[12:13], s[0:1], v15, s20, v[2:3]
	ds_read_b64 v[8:9], v8 offset:49152
	ds_read_b64 v[10:11], v10 offset:49152
	ds_read_b64 v[12:13], v12 offset:49152
	s_waitcnt lgkmcnt(3)
	global_store_dwordx2 v[6:7], v[4:5], off
	v_add_u32_e32 v4, s25, v3
	v_ashrrev_i32_e32 v5, 31, v4
	v_lshlrev_b64 v[4:5], 12, v[4:5]
	v_lshl_add_u64 v[4:5], v[0:1], 0, v[4:5]
	s_waitcnt lgkmcnt(2)
	global_store_dwordx2 v[4:5], v[8:9], off
	v_add_u32_e32 v4, s25, v14
	v_ashrrev_i32_e32 v5, 31, v4
	v_lshlrev_b64 v[4:5], 12, v[4:5]
	v_lshl_add_u64 v[4:5], v[0:1], 0, v[4:5]
	s_waitcnt lgkmcnt(1)
	global_store_dwordx2 v[4:5], v[10:11], off
	v_add_u32_e32 v4, s25, v15
	v_ashrrev_i32_e32 v5, 31, v4
	v_lshlrev_b64 v[4:5], 12, v[4:5]
	v_lshl_add_u64 v[4:5], v[0:1], 0, v[4:5]
	v_ashrrev_i32_e32 v3, 7, v83
	s_waitcnt lgkmcnt(0)
	global_store_dwordx2 v[4:5], v[12:13], off
	v_mad_u64_u32 v[4:5], s[0:1], v3, s20, v[2:3]
	ds_read_b64 v[4:5], v4 offset:49152
	v_add_u32_e32 v6, s25, v3
	v_ashrrev_i32_e32 v7, 31, v6
	v_lshlrev_b64 v[6:7], 12, v[6:7]
	v_ashrrev_i32_e32 v3, 7, v86
	v_ashrrev_i32_e32 v14, 7, v85
	v_ashrrev_i32_e32 v15, 7, v84
	v_lshl_add_u64 v[6:7], v[0:1], 0, v[6:7]
	v_mad_u64_u32 v[8:9], s[0:1], v3, s20, v[2:3]
	v_mad_u64_u32 v[10:11], s[0:1], v14, s20, v[2:3]
	v_mad_u64_u32 v[12:13], s[0:1], v15, s20, v[2:3]
	ds_read_b64 v[8:9], v8 offset:49152
	ds_read_b64 v[10:11], v10 offset:49152
	ds_read_b64 v[12:13], v12 offset:49152
	s_waitcnt lgkmcnt(3)
	global_store_dwordx2 v[6:7], v[4:5], off
	v_add_u32_e32 v4, s25, v3
	v_ashrrev_i32_e32 v5, 31, v4
	v_lshlrev_b64 v[4:5], 12, v[4:5]
	v_lshl_add_u64 v[4:5], v[0:1], 0, v[4:5]
	s_waitcnt lgkmcnt(2)
	global_store_dwordx2 v[4:5], v[8:9], off
	v_add_u32_e32 v4, s25, v14
	v_ashrrev_i32_e32 v5, 31, v4
	v_lshlrev_b64 v[4:5], 12, v[4:5]
	v_lshl_add_u64 v[4:5], v[0:1], 0, v[4:5]
	s_waitcnt lgkmcnt(1)
	global_store_dwordx2 v[4:5], v[10:11], off
	v_add_u32_e32 v4, s25, v15
	v_ashrrev_i32_e32 v5, 31, v4
	v_lshlrev_b64 v[4:5], 12, v[4:5]
	v_add_u32_e32 v3, 0x1000, v79
	v_lshl_add_u64 v[4:5], v[0:1], 0, v[4:5]
	v_ashrrev_i32_e32 v3, 7, v3
	s_waitcnt lgkmcnt(0)
	global_store_dwordx2 v[4:5], v[12:13], off
	v_mad_u64_u32 v[4:5], s[0:1], v3, s20, v[2:3]
	v_add_u32_e32 v6, s25, v3
	v_add_u32_e32 v3, 0x1200, v79
	v_ashrrev_i32_e32 v3, 7, v3
	ds_read_b64 v[4:5], v4 offset:49152
	v_mad_u64_u32 v[8:9], s[0:1], v3, s20, v[2:3]
	v_add_u32_e32 v9, 0x1400, v79
	v_ashrrev_i32_e32 v7, 31, v6
	v_ashrrev_i32_e32 v14, 7, v9
	v_add_u32_e32 v9, 0x1600, v79
	v_lshlrev_b64 v[6:7], 12, v[6:7]
	v_ashrrev_i32_e32 v15, 7, v9
	v_lshl_add_u64 v[6:7], v[0:1], 0, v[6:7]
	v_mad_u64_u32 v[10:11], s[0:1], v14, s20, v[2:3]
	v_mad_u64_u32 v[12:13], s[0:1], v15, s20, v[2:3]
	ds_read_b64 v[8:9], v8 offset:49152
	ds_read_b64 v[10:11], v10 offset:49152
	ds_read_b64 v[12:13], v12 offset:49152
	s_waitcnt lgkmcnt(3)
	global_store_dwordx2 v[6:7], v[4:5], off
	v_add_u32_e32 v4, s25, v3
	v_ashrrev_i32_e32 v5, 31, v4
	v_lshlrev_b64 v[4:5], 12, v[4:5]
	v_lshl_add_u64 v[4:5], v[0:1], 0, v[4:5]
	s_waitcnt lgkmcnt(2)
	global_store_dwordx2 v[4:5], v[8:9], off
	v_add_u32_e32 v4, s25, v14
	v_ashrrev_i32_e32 v5, 31, v4
	v_lshlrev_b64 v[4:5], 12, v[4:5]
	v_lshl_add_u64 v[4:5], v[0:1], 0, v[4:5]
	s_waitcnt lgkmcnt(1)
	global_store_dwordx2 v[4:5], v[10:11], off
	v_add_u32_e32 v4, s25, v15
	v_ashrrev_i32_e32 v5, 31, v4
	v_lshlrev_b64 v[4:5], 12, v[4:5]
	v_add_u32_e32 v3, 0x1800, v79
	v_lshl_add_u64 v[4:5], v[0:1], 0, v[4:5]
	v_ashrrev_i32_e32 v3, 7, v3
	s_waitcnt lgkmcnt(0)
	global_store_dwordx2 v[4:5], v[12:13], off
	v_mad_u64_u32 v[4:5], s[0:1], v3, s20, v[2:3]
	v_add_u32_e32 v6, s25, v3
	v_add_u32_e32 v3, 0x1a00, v79
	v_ashrrev_i32_e32 v12, 7, v3
	ds_read_b64 v[4:5], v4 offset:49152
	v_mad_u64_u32 v[8:9], s[0:1], v12, s20, v[2:3]
	v_add_u32_e32 v3, 0x1c00, v79
	v_ashrrev_i32_e32 v13, 7, v3
	v_ashrrev_i32_e32 v7, 31, v6
	v_mad_u64_u32 v[10:11], s[0:1], v13, s20, v[2:3]
	v_add_u32_e32 v3, 0x1e00, v79
	v_lshlrev_b64 v[6:7], 12, v[6:7]
	v_ashrrev_i32_e32 v14, 7, v3
	v_lshl_add_u64 v[6:7], v[0:1], 0, v[6:7]
	v_mad_u64_u32 v[2:3], s[0:1], v14, s20, v[2:3]
	ds_read_b64 v[8:9], v8 offset:49152
	ds_read_b64 v[10:11], v10 offset:49152
	ds_read_b64 v[2:3], v2 offset:49152
	s_waitcnt lgkmcnt(3)
	global_store_dwordx2 v[6:7], v[4:5], off
	v_add_u32_e32 v4, s25, v12
	v_ashrrev_i32_e32 v5, 31, v4
	v_lshlrev_b64 v[4:5], 12, v[4:5]
	v_lshl_add_u64 v[4:5], v[0:1], 0, v[4:5]
	s_waitcnt lgkmcnt(2)
	global_store_dwordx2 v[4:5], v[8:9], off
	v_add_u32_e32 v4, s25, v13
	v_ashrrev_i32_e32 v5, 31, v4
	v_lshlrev_b64 v[4:5], 12, v[4:5]
	v_lshl_add_u64 v[4:5], v[0:1], 0, v[4:5]
	s_waitcnt lgkmcnt(1)
	global_store_dwordx2 v[4:5], v[10:11], off
	v_add_u32_e32 v4, s25, v14
	v_ashrrev_i32_e32 v5, 31, v4
	v_readlane_b32 s0, v237, 27
	v_lshlrev_b64 v[4:5], 12, v[4:5]
	s_add_i32 s6, s6, s84
	s_add_i32 s12, s12, s0
	s_add_i32 s13, s13, s16
	s_add_i32 s24, s24, s72
	v_lshl_add_u64 v[0:1], v[0:1], 0, v[4:5]
	s_cmpk_gt_i32 s6, 0x1ff
	s_waitcnt lgkmcnt(0)
	global_store_dwordx2 v[0:1], v[2:3], off
	s_barrier
	s_cbranch_scc1 .LBB0_519
; #define LAS __attribute__((address_space(3)))
; __device__ __forceinline__ bf16* st_ptr(unsigned char* ws, int pu) { return (bf16*)(ws + (pu < 392 ? WS_ST0 + (size_t)pu * 262144 : WS_ST1 + (size_t)(pu - 392) * 262144)); }
; __device__ __forceinline__ void gla_out_unit(const Params& P, LAS unsigned char* lds, int u) {
;     ...
;     bf16* OB = (bf16*)(ws + WS_OB); const bf16* ST = st_ptr(ws, u);
;     LAS bf16* QS = (LAS bf16*)lds;
;     LAS bf16* AS = (LAS bf16*)(lds + 33792);
;     LAS float* SS = (LAS float*)(lds + 33792 + 9216);
;     LAS float* RS = (LAS float*)(lds + 33792 + 9216 + 2048);
; #pragma unroll
;     for (int it = 0; it < 4; ++it) { const int idx = it * NTHREADS + tid, t = idx >> 5, cc = idx & 31; *(LAS v4u*)(QS + t * 264 + 8 * cc) = *(const v4u*)(QT + ((size_t)u * 64 + t) * 256 + 8 * cc); }
;     { const int t = tid >> 3, cc = tid & 7; *(LAS v4u*)(AS + t * 72 + 8 * cc) = *(const v4u*)(AM + ((size_t)u * 64 + t) * 64 + 8 * cc); }
;     LAS bf16* RT = (LAS bf16*)(lds + 49152);
; #pragma unroll
;     for (int it = 0; it < 8; ++it) { const int idx = it * NTHREADS + tid, t = idx >> 6, cc = idx & 63; const v4u rv = *(const v4u*)(PROJ + (size_t)(tok0 + t) * LD0 + 4096 + 512 * h + 8 * cc);
;         LAS v2u* d = (LAS v2u*)(RT + t * 516 + 8 * cc); d[0] = (v2u){rv.x, rv.y}; d[1] = (v2u){rv.z, rv.w}; }
;     __syncthreads();
;     f32x4 acc[4][4];
; #pragma unroll
;     for (int m = 0; m < 4; ++m)
; #pragma unroll
;         for (int j = 0; j < 4; ++j) acc[m][j] = (f32x4){0.f, 0.f, 0.f, 0.f};
;     const bf16* stp = ST + ((size_t)(q4 >> 1) * 512 + 64 * wave + fr) * 16 + 8 * (q4 & 1); const bf16* vtp = VT + ((size_t)u * 512 + 64 * wave + fr) * 64 + 8 * q4;
; #pragma unroll
;     for (int kb = 0; kb < 10; ++kb) { bf16x8 bfr[4], afr[4];
; #pragma unroll
;         for (int j = 0; j < 4; ++j) bfr[j] = kb < 8 ? __builtin_nontemporal_load((const bf16x8*)(stp + (size_t)(2 * kb) * 8192 + 16 * j * 16)) : *(const bf16x8*)(vtp + (size_t)(16 * j) * 64 + 32 * (kb - 8));
.LBB0_485:
	s_and_b32 s4, s13, 0xfc0
	s_add_i32 s0, s6, 0xfffffe78
	s_ashr_i32 s7, s6, 31
	s_cmpk_lt_i32 s6, 0x188
	s_cselect_b32 s3, s7, 0
	s_cselect_b32 s2, s6, s0
	s_mov_b32 s0, 0x9200000
	s_cselect_b32 s0, s0, 0x1b800000
	s_lshl_b64 s[2:3], s[2:3], 18
	s_add_u32 s1, s90, s2
	v_mov_b32_e32 v79, v172
	s_addc_u32 s2, s91, s3
	s_cmp_lg_u32 s30, 0
	s_cbranch_scc1 .Lmy_p4_skiph
	s_add_u32 s28, s1, s0
	s_addc_u32 s29, s2, 0
	v_and_b32_e32 v255, 0xffffffc0, v172
	v_lshlrev_b32_e32 v254, 4, v172
	v_and_b32_e32 v254, 0x200, v254
	v_add_u32_e32 v255, v255, v254
	v_and_b32_e32 v254, 15, v172
	v_or_b32_e32 v255, v255, v254
	v_lshlrev_b32_e32 v255, 5, v255
	v_and_b32_e32 v254, 16, v172
	v_add_u32_e32 v255, v255, v254
	global_load_dwordx4 v[142:145], v255, s[28:29]
	global_load_dwordx4 v[146:149], v255, s[28:29] offset:512
	global_load_dwordx4 v[150:153], v255, s[28:29] offset:1024
	global_load_dwordx4 v[154:157], v255, s[28:29] offset:1536
	v_add_u32_e32 v255, 0x8000, v255
	global_load_dwordx4 v[158:161], v255, s[28:29]
	global_load_dwordx4 v[162:165], v255, s[28:29] offset:512
	global_load_dwordx4 v[166:169], v255, s[28:29] offset:1024
	global_load_dwordx4 v[180:183], v255, s[28:29] offset:1536
	v_add_u32_e32 v255, 0x8000, v255
	global_load_dwordx4 v[184:187], v255, s[28:29]
	global_load_dwordx4 v[188:191], v255, s[28:29] offset:512
	global_load_dwordx4 v[192:195], v255, s[28:29] offset:1024
	global_load_dwordx4 v[196:199], v255, s[28:29] offset:1536
	v_add_u32_e32 v255, 0x8000, v255
	global_load_dwordx4 v[200:203], v255, s[28:29]
	global_load_dwordx4 v[204:207], v255, s[28:29] offset:512
	global_load_dwordx4 v[208:211], v255, s[28:29] offset:1024
	global_load_dwordx4 v[212:215], v255, s[28:29] offset:1536
	v_add_u32_e32 v255, 0x8000, v255
	global_load_dwordx4 v[216:219], v255, s[28:29]
	global_load_dwordx4 v[220:223], v255, s[28:29] offset:512
	global_load_dwordx4 v[224:227], v255, s[28:29] offset:1024
	global_load_dwordx4 v[228:231], v255, s[28:29] offset:1536
	v_add_u32_e32 v255, 0x8000, v255
	global_load_dwordx4 v[232:235], v255, s[28:29]
	global_load_dwordx4 v[238:241], v255, s[28:29] offset:512
	global_load_dwordx4 v[242:245], v255, s[28:29] offset:1024
	global_load_dwordx4 v[246:249], v255, s[28:29] offset:1536
	v_add_u32_e32 v255, 0x8000, v255
.Lmy_p4_skiph:
	s_lshl_b64 s[26:27], s[6:7], 15
	s_add_u32 s26, s59, s26
	v_lshlrev_b32_e32 v53, 4, v79
	v_add_u32_e32 v81, 0x400, v79
	s_addc_u32 s27, s60, s27
	v_and_b32_e32 v68, 0x1f0, v53
	v_ashrrev_i32_e32 v54, 5, v79
	v_add_u32_e32 v82, 0x200, v79
	v_ashrrev_i32_e32 v58, 5, v81
	s_and_b32 s3, s12, 0xfffff000
	v_ashrrev_i32_e32 v20, 3, v79
	v_lshl_add_u64 v[12:13], s[26:27], 0, v[68:69]
	v_ashrrev_i32_e32 v55, 31, v54
	v_ashrrev_i32_e32 v56, 5, v82
	v_ashrrev_i32_e32 v59, 31, v58
	v_add_u32_e32 v80, 0x600, v79
	s_or_b32 s25, s3, s4
	v_ashrrev_i32_e32 v21, 31, v20
	s_lshl_b64 s[26:27], s[6:7], 13
	s_movk_i32 s3, 0x90
	v_add_u32_e32 v52, 0, v68
	v_lshlrev_b64 v[0:1], 9, v[54:55]
	v_ashrrev_i32_e32 v57, 31, v56
	v_lshlrev_b64 v[8:9], 9, v[58:59]
	v_ashrrev_i32_e32 v60, 5, v80
	s_add_u32 s26, s61, s26
	v_lshlrev_b64 v[16:17], 7, v[20:21]
	v_and_b32_e32 v68, 0x70, v53
	v_mul_lo_u32 v20, v20, s3
	v_ashrrev_i32_e32 v59, 6, v79
	v_lshl_add_u64 v[0:1], v[12:13], 0, v[0:1]
	v_lshlrev_b64 v[4:5], 9, v[56:57]
	v_ashrrev_i32_e32 v61, 31, v60
	s_addc_u32 s27, s62, s27
	v_add3_u32 v57, 0, v20, v68
	s_and_b32 s3, s24, 0x600
	v_add_u32_e32 v20, s25, v59
	global_load_dwordx4 v[0:3], v[0:1], off
	v_lshl_add_u64 v[4:5], v[12:13], 0, v[4:5]
	v_lshlrev_b64 v[14:15], 9, v[60:61]
	v_lshl_add_u64 v[16:17], s[26:27], 0, v[16:17]
	v_mad_i64_i32 v[20:21], s[26:27], v20, s18, v[70:71]
	s_lshl_b32 s4, s3, 1
	v_ashrrev_i32_e32 v61, 6, v82
	global_load_dwordx4 v[4:7], v[4:5], off
	v_lshl_add_u64 v[8:9], v[12:13], 0, v[8:9]
	v_lshl_add_u64 v[16:17], v[16:17], 0, v[68:69]
	v_and_b32_e32 v68, 0x3f0, v53
	v_lshl_add_u64 v[20:21], v[20:21], 0, s[4:5]
	v_add_u32_e32 v24, s25, v61
	global_load_dwordx4 v[8:11], v[8:9], off
	v_lshl_add_u64 v[12:13], v[12:13], 0, v[14:15]
	v_lshl_add_u64 v[20:21], v[20:21], 0, v[68:69]
	v_mad_i64_i32 v[24:25], s[26:27], v24, s18, v[70:71]
	v_ashrrev_i32_e32 v62, 6, v81
	global_load_dwordx4 v[12:15], v[12:13], off
	v_add_co_u32_e32 v20, vcc, s19, v20
	v_lshl_add_u64 v[24:25], v[24:25], 0, s[4:5]
	v_add_u32_e32 v28, s25, v62
	v_addc_co_u32_e32 v21, vcc, 0, v21, vcc
	v_lshl_add_u64 v[24:25], v[24:25], 0, v[68:69]
	v_mad_i64_i32 v[28:29], s[26:27], v28, s18, v[70:71]
	v_ashrrev_i32_e32 v63, 6, v80
	global_load_dwordx4 v[16:19], v[16:17], off
	v_add_co_u32_e32 v24, vcc, s19, v24
	global_load_dwordx4 v[20:23], v[20:21], off
	v_lshl_add_u64 v[28:29], v[28:29], 0, s[4:5]
	v_add_u32_e32 v32, s25, v63
	v_add_u32_e32 v83, 0x800, v79
	v_addc_co_u32_e32 v25, vcc, 0, v25, vcc
	v_lshl_add_u64 v[28:29], v[28:29], 0, v[68:69]
	v_mad_i64_i32 v[32:33], s[26:27], v32, s18, v[70:71]
	v_ashrrev_i32_e32 v64, 6, v83
	global_load_dwordx4 v[24:27], v[24:25], off
	v_add_co_u32_e32 v28, vcc, s19, v28
	v_lshl_add_u64 v[32:33], v[32:33], 0, s[4:5]
	v_add_u32_e32 v36, s25, v64
	v_add_u32_e32 v86, 0xa00, v79
	v_addc_co_u32_e32 v29, vcc, 0, v29, vcc
	v_lshl_add_u64 v[32:33], v[32:33], 0, v[68:69]
	v_mad_i64_i32 v[36:37], s[26:27], v36, s18, v[70:71]
	v_ashrrev_i32_e32 v65, 6, v86
	global_load_dwordx4 v[28:31], v[28:29], off
	v_add_co_u32_e32 v32, vcc, s19, v32
	v_lshl_add_u64 v[36:37], v[36:37], 0, s[4:5]
	v_add_u32_e32 v40, s25, v65
	v_add_u32_e32 v85, 0xc00, v79
	v_addc_co_u32_e32 v33, vcc, 0, v33, vcc
	v_lshl_add_u64 v[36:37], v[36:37], 0, v[68:69]
	v_mad_i64_i32 v[40:41], s[26:27], v40, s18, v[70:71]
	v_ashrrev_i32_e32 v66, 6, v85
	global_load_dwordx4 v[32:35], v[32:33], off
	v_add_co_u32_e32 v36, vcc, s19, v36
	v_lshl_add_u64 v[40:41], v[40:41], 0, s[4:5]
	v_add_u32_e32 v44, s25, v66
	v_add_u32_e32 v84, 0xe00, v79
	v_addc_co_u32_e32 v37, vcc, 0, v37, vcc
	v_lshl_add_u64 v[40:41], v[40:41], 0, v[68:69]
	v_mad_i64_i32 v[44:45], s[26:27], v44, s18, v[70:71]
	v_ashrrev_i32_e32 v67, 6, v84
	global_load_dwordx4 v[36:39], v[36:37], off
	v_add_co_u32_e32 v40, vcc, s19, v40
	v_lshl_add_u64 v[44:45], v[44:45], 0, s[4:5]
	v_add_u32_e32 v48, s25, v67
	v_addc_co_u32_e32 v41, vcc, 0, v41, vcc
	v_lshl_add_u64 v[44:45], v[44:45], 0, v[68:69]
	v_mad_i64_i32 v[48:49], s[26:27], v48, s18, v[70:71]
	global_load_dwordx4 v[40:43], v[40:41], off
	v_add_co_u32_e32 v44, vcc, s19, v44
	v_lshl_add_u64 v[48:49], v[48:49], 0, s[4:5]
	s_nop 0
	v_addc_co_u32_e32 v45, vcc, 0, v45, vcc
	v_lshl_add_u64 v[48:49], v[48:49], 0, v[68:69]
	global_load_dwordx4 v[44:47], v[44:45], off
	v_add_co_u32_e32 v48, vcc, s19, v48
	v_mad_u64_u32 v[54:55], s[26:27], v54, s17, v[52:53]
	s_nop 0
	v_addc_co_u32_e32 v49, vcc, 0, v49, vcc
	global_load_dwordx4 v[48:51], v[48:49], off
	s_waitcnt vmcnt(12)
; #define LAS __attribute__((address_space(3)))
; __device__ __forceinline__ void gla_out_unit(const Params& P, LAS unsigned char* lds, int u) {
;     ...
; #pragma unroll
;     for (int it = 0; it < 4; ++it) { const int idx = it * NTHREADS + tid, t = idx >> 5, cc = idx & 31; *(LAS v4u*)(QS + t * 264 + 8 * cc) = *(const v4u*)(QT + ((size_t)u * 64 + t) * 256 + 8 * cc); }
;     { const int t = tid >> 3, cc = tid & 7; *(LAS v4u*)(AS + t * 72 + 8 * cc) = *(const v4u*)(AM + ((size_t)u * 64 + t) * 64 + 8 * cc); }
;     LAS bf16* RT = (LAS bf16*)(lds + 49152);
; #pragma unroll
;     for (int it = 0; it < 8; ++it) { const int idx = it * NTHREADS + tid, t = idx >> 6, cc = idx & 63; const v4u rv = *(const v4u*)(PROJ + (size_t)(tok0 + t) * LD0 + 4096 + 512 * h + 8 * cc);
;         LAS v2u* d = (LAS v2u*)(RT + t * 516 + 8 * cc); d[0] = (v2u){rv.x, rv.y}; d[1] = (v2u){rv.z, rv.w}; }
;     __syncthreads();
;     f32x4 acc[4][4];
; #pragma unroll
;     for (int m = 0; m < 4; ++m)
; #pragma unroll
;         for (int j = 0; j < 4; ++j) acc[m][j] = (f32x4){0.f, 0.f, 0.f, 0.f};
;     const bf16* stp = ST + ((size_t)(q4 >> 1) * 512 + 64 * wave + fr) * 16 + 8 * (q4 & 1); const bf16* vtp = VT + ((size_t)u * 512 + 64 * wave + fr) * 64 + 8 * q4;
; #pragma unroll
;     for (int kb = 0; kb < 10; ++kb) { bf16x8 bfr[4], afr[4];
; #pragma unroll
;         for (int j = 0; j < 4; ++j) bfr[j] = kb < 8 ? __builtin_nontemporal_load((const bf16x8*)(stp + (size_t)(2 * kb) * 8192 + 16 * j * 16)) : *(const bf16x8*)(vtp + (size_t)(16 * j) * 64 + 32 * (kb - 8));
; #pragma unroll
;         for (int m = 0; m < 4; ++m) afr[m] = kb < 8 ? *(const LAS bf16x8*)(QS + (16 * m + fr) * 264 + 32 * kb + 8 * q4) : *(const LAS bf16x8*)(AS + (16 * m + fr) * 72 + 32 * (kb - 8) + 8 * q4);
; #pragma unroll
;         for (int m = 0; m < 4; ++m)
; #pragma unroll
;             for (int j = 0; j < 4; ++j) acc[m][j] = __builtin_amdgcn_mfma_f32_16x16x32_bf16(afr[m], bfr[j], acc[m][j], 0, 0, 0); }
	ds_write_b128 v54, v[0:3]
	v_mad_u64_u32 v[0:1], s[26:27], v56, s17, v[52:53]
	s_waitcnt vmcnt(11)
	ds_write_b128 v0, v[4:7]
	v_mad_u64_u32 v[0:1], s[26:27], v58, s17, v[52:53]
	s_waitcnt vmcnt(10)
	ds_write_b128 v0, v[8:11]
	v_mad_u64_u32 v[0:1], s[26:27], v60, s17, v[52:53]
	s_waitcnt vmcnt(9)
	ds_write_b128 v0, v[12:15]
	v_add_u32_e32 v0, 0, v68
	v_mul_lo_u32 v1, v59, s20
	v_add3_u32 v1, v0, v1, s21
	s_waitcnt vmcnt(8)
	ds_write_b128 v57, v[16:19] offset:33792
	s_waitcnt vmcnt(7)
	ds_write2_b64 v1, v[20:21], v[22:23] offset1:1
	v_mul_lo_u32 v1, v61, s20
	v_add3_u32 v1, v0, v1, s21
	v_and_b32_e32 v72, 0xffffffc0, v79
	v_and_b32_e32 v68, 0x200, v53
	s_waitcnt vmcnt(6)
	ds_write2_b64 v1, v[24:25], v[26:27] offset1:1
	v_mul_lo_u32 v1, v62, s20
	v_add3_u32 v1, v0, v1, s21
	v_ashrrev_i32_e32 v73, 31, v72
	v_and_b32_e32 v91, 15, v79
	s_add_u32 s0, s1, s0
	s_addc_u32 s1, s2, 0
	v_bfe_u32 v92, v79, 4, 2
	s_waitcnt vmcnt(5)
	ds_write2_b64 v1, v[28:29], v[30:31] offset1:1
	v_mul_lo_u32 v1, v63, s20
	v_add3_u32 v1, v0, v1, s21
	s_waitcnt vmcnt(4)
	ds_write2_b64 v1, v[32:33], v[34:35] offset1:1
	v_mul_lo_u32 v1, v64, s20
	v_add3_u32 v1, v0, v1, s21
	s_waitcnt vmcnt(3)
	ds_write2_b64 v1, v[36:37], v[38:39] offset1:1
	v_mul_lo_u32 v1, v65, s20
	v_add3_u32 v1, v0, v1, s21
	s_waitcnt vmcnt(2)
	ds_write2_b64 v1, v[40:41], v[42:43] offset1:1
	v_mul_lo_u32 v1, v66, s20
	v_add3_u32 v1, v0, v1, s21
	s_waitcnt vmcnt(1)
	ds_write2_b64 v1, v[44:45], v[46:47] offset1:1
	v_mul_lo_u32 v1, v67, s20
	v_add3_u32 v0, v0, v1, s21
	s_waitcnt vmcnt(0)
	ds_write2_b64 v0, v[48:49], v[50:51] offset1:1
	v_lshl_add_u64 v[0:1], v[68:69], 0, v[72:73]
	v_or_b32_e32 v0, v0, v91
	v_lshlrev_b64 v[0:1], 5, v[0:1]
	v_lshl_add_u64 v[0:1], s[0:1], 0, v[0:1]
	v_and_b32_e32 v68, 16, v79
	v_lshl_add_u64 v[16:17], v[0:1], 0, v[68:69]
	s_waitcnt lgkmcnt(0)
	s_barrier
	v_lshlrev_b32_e32 v68, 4, v92
	v_add_u32_e32 v87, 0, v68
	v_mad_u32_u24 v18, v91, s17, v87
	ds_read_b128 v[4:7], v18
	ds_read_b128 v[98:101], v18 offset:25344
	s_waitcnt lgkmcnt(1)
	v_mfma_f32_16x16x32_bf16 v[20:23], v[4:7], v[142:145], 0
	s_mov_b32 s0, 0x8000
	v_add_co_u32_e32 v88, vcc, s0, v16
	v_mfma_f32_16x16x32_bf16 v[24:27], v[4:7], v[146:149], 0
	v_addc_co_u32_e32 v89, vcc, 0, v17, vcc
	v_mfma_f32_16x16x32_bf16 v[28:31], v[4:7], v[150:153], 0
	ds_read_b128 v[114:117], v18 offset:25792
	v_mfma_f32_16x16x32_bf16 v[36:39], v[4:7], v[154:157], 0
	ds_read_b128 v[4:7], v18 offset:8448
	s_mov_b32 s0, 0x10000
	s_waitcnt lgkmcnt(0)
	v_mfma_f32_16x16x32_bf16 v[40:43], v[4:7], v[142:145], 0
	v_mfma_f32_16x16x32_bf16 v[44:47], v[4:7], v[146:149], 0
	v_mfma_f32_16x16x32_bf16 v[48:51], v[4:7], v[150:153], 0
	v_mfma_f32_16x16x32_bf16 v[52:55], v[4:7], v[154:157], 0
	ds_read_b128 v[4:7], v18 offset:16896
	s_waitcnt lgkmcnt(0)
	v_mfma_f32_16x16x32_bf16 v[56:59], v[4:7], v[142:145], 0
	v_mfma_f32_16x16x32_bf16 v[60:63], v[4:7], v[146:149], 0
	v_mfma_f32_16x16x32_bf16 v[64:67], v[4:7], v[150:153], 0
	v_mfma_f32_16x16x32_bf16 v[94:97], v[4:7], v[154:157], 0
	v_mfma_f32_16x16x32_bf16 v[4:7], v[98:101], v[142:145], 0
	v_mfma_f32_16x16x32_bf16 v[8:11], v[98:101], v[146:149], 0
	v_mfma_f32_16x16x32_bf16 v[12:15], v[98:101], v[150:153], 0
	v_mfma_f32_16x16x32_bf16 v[0:3], v[98:101], v[154:157], 0
	global_load_dwordx4 v[142:145], v255, s[28:29]
	global_load_dwordx4 v[146:149], v255, s[28:29] offset:512
	global_load_dwordx4 v[150:153], v255, s[28:29] offset:1024
	global_load_dwordx4 v[154:157], v255, s[28:29] offset:1536
	v_add_u32_e32 v255, 0x8000, v255
	ds_read_b128 v[32:35], v18 offset:64
	v_add_co_u32_e32 v88, vcc, s0, v16
	s_waitcnt lgkmcnt(0)
	v_mfma_f32_16x16x32_bf16 v[20:23], v[32:35], v[158:161], v[20:23]
	v_addc_co_u32_e32 v89, vcc, 0, v17, vcc
	s_mov_b32 s0, 0x18000
	v_mfma_f32_16x16x32_bf16 v[24:27], v[32:35], v[162:165], v[24:27]
	v_mfma_f32_16x16x32_bf16 v[28:31], v[32:35], v[166:169], v[28:31]
	v_mfma_f32_16x16x32_bf16 v[32:35], v[32:35], v[180:183], v[36:39]
	s_nop 2
	ds_read_b128 v[36:39], v18 offset:8512
	s_waitcnt lgkmcnt(0)
	v_mfma_f32_16x16x32_bf16 v[40:43], v[36:39], v[158:161], v[40:43]
	v_mfma_f32_16x16x32_bf16 v[44:47], v[36:39], v[162:165], v[44:47]
	v_mfma_f32_16x16x32_bf16 v[48:51], v[36:39], v[166:169], v[48:51]
	v_mfma_f32_16x16x32_bf16 v[36:39], v[36:39], v[180:183], v[52:55]
	s_nop 2
	ds_read_b128 v[52:55], v18 offset:16960
	s_waitcnt lgkmcnt(0)
	v_mfma_f32_16x16x32_bf16 v[56:59], v[52:55], v[158:161], v[56:59]
	v_mfma_f32_16x16x32_bf16 v[60:63], v[52:55], v[162:165], v[60:63]
	v_mfma_f32_16x16x32_bf16 v[64:67], v[52:55], v[166:169], v[64:67]
	v_mfma_f32_16x16x32_bf16 v[52:55], v[52:55], v[180:183], v[94:97]
	s_nop 2
	ds_read_b128 v[94:97], v18 offset:25408
	s_waitcnt lgkmcnt(0)
	v_mfma_f32_16x16x32_bf16 v[4:7], v[94:97], v[158:161], v[4:7]
	v_mfma_f32_16x16x32_bf16 v[8:11], v[94:97], v[162:165], v[8:11]
	v_mfma_f32_16x16x32_bf16 v[12:15], v[94:97], v[166:169], v[12:15]
	v_mfma_f32_16x16x32_bf16 v[0:3], v[94:97], v[180:183], v[0:3]
	global_load_dwordx4 v[158:161], v255, s[28:29]
	global_load_dwordx4 v[162:165], v255, s[28:29] offset:512
	global_load_dwordx4 v[166:169], v255, s[28:29] offset:1024
	global_load_dwordx4 v[180:183], v255, s[28:29] offset:1536
	v_add_u32_e32 v255, 0x8000, v255
	ds_read_b128 v[94:97], v18 offset:128
	v_add_co_u32_e32 v88, vcc, s0, v16
	s_waitcnt lgkmcnt(0)
	v_mfma_f32_16x16x32_bf16 v[20:23], v[94:97], v[184:187], v[20:23]
	v_addc_co_u32_e32 v89, vcc, 0, v17, vcc
	s_mov_b32 s0, 0x20000
	v_mfma_f32_16x16x32_bf16 v[24:27], v[94:97], v[188:191], v[24:27]
	v_mfma_f32_16x16x32_bf16 v[28:31], v[94:97], v[192:195], v[28:31]
	v_mfma_f32_16x16x32_bf16 v[32:35], v[94:97], v[196:199], v[32:35]
	ds_read_b128 v[94:97], v18 offset:8576
	s_waitcnt lgkmcnt(0)
; #define LAS __attribute__((address_space(3)))
; __device__ __forceinline__ void gla_out_unit(const Params& P, LAS unsigned char* lds, int u) {
;     ...
;     for (int kb = 0; kb < 10; ++kb) { bf16x8 bfr[4], afr[4];
; #pragma unroll
;         for (int j = 0; j < 4; ++j) bfr[j] = kb < 8 ? __builtin_nontemporal_load((const bf16x8*)(stp + (size_t)(2 * kb) * 8192 + 16 * j * 16)) : *(const bf16x8*)(vtp + (size_t)(16 * j) * 64 + 32 * (kb - 8));
; #pragma unroll
;         for (int m = 0; m < 4; ++m) afr[m] = kb < 8 ? *(const LAS bf16x8*)(QS + (16 * m + fr) * 264 + 32 * kb + 8 * q4) : *(const LAS bf16x8*)(AS + (16 * m + fr) * 72 + 32 * (kb - 8) + 8 * q4);
; #pragma unroll
;         for (int m = 0; m < 4; ++m)
; #pragma unroll
;             for (int j = 0; j < 4; ++j) acc[m][j] = __builtin_amdgcn_mfma_f32_16x16x32_bf16(afr[m], bfr[j], acc[m][j], 0, 0, 0); }
	v_mfma_f32_16x16x32_bf16 v[40:43], v[94:97], v[184:187], v[40:43]
	v_mfma_f32_16x16x32_bf16 v[44:47], v[94:97], v[188:191], v[44:47]
	v_mfma_f32_16x16x32_bf16 v[48:51], v[94:97], v[192:195], v[48:51]
	v_mfma_f32_16x16x32_bf16 v[36:39], v[94:97], v[196:199], v[36:39]
	ds_read_b128 v[94:97], v18 offset:17024
	s_waitcnt lgkmcnt(0)
	v_mfma_f32_16x16x32_bf16 v[56:59], v[94:97], v[184:187], v[56:59]
	v_mfma_f32_16x16x32_bf16 v[60:63], v[94:97], v[188:191], v[60:63]
	v_mfma_f32_16x16x32_bf16 v[64:67], v[94:97], v[192:195], v[64:67]
	v_mfma_f32_16x16x32_bf16 v[52:55], v[94:97], v[196:199], v[52:55]
	ds_read_b128 v[94:97], v18 offset:25472
	s_waitcnt lgkmcnt(0)
	v_mfma_f32_16x16x32_bf16 v[4:7], v[94:97], v[184:187], v[4:7]
	v_mfma_f32_16x16x32_bf16 v[8:11], v[94:97], v[188:191], v[8:11]
	v_mfma_f32_16x16x32_bf16 v[12:15], v[94:97], v[192:195], v[12:15]
	v_mfma_f32_16x16x32_bf16 v[0:3], v[94:97], v[196:199], v[0:3]
	ds_read_b128 v[94:97], v18 offset:192
	v_add_co_u32_e32 v88, vcc, s0, v16
	s_waitcnt lgkmcnt(0)
	v_mfma_f32_16x16x32_bf16 v[20:23], v[94:97], v[200:203], v[20:23]
	v_addc_co_u32_e32 v89, vcc, 0, v17, vcc
	s_mov_b32 s0, 0x28000
	v_mfma_f32_16x16x32_bf16 v[24:27], v[94:97], v[204:207], v[24:27]
	v_mfma_f32_16x16x32_bf16 v[28:31], v[94:97], v[208:211], v[28:31]
	v_mfma_f32_16x16x32_bf16 v[32:35], v[94:97], v[212:215], v[32:35]
	ds_read_b128 v[94:97], v18 offset:8640
	s_waitcnt lgkmcnt(0)
	v_mfma_f32_16x16x32_bf16 v[40:43], v[94:97], v[200:203], v[40:43]
	v_mfma_f32_16x16x32_bf16 v[44:47], v[94:97], v[204:207], v[44:47]
	v_mfma_f32_16x16x32_bf16 v[48:51], v[94:97], v[208:211], v[48:51]
	v_mfma_f32_16x16x32_bf16 v[36:39], v[94:97], v[212:215], v[36:39]
	ds_read_b128 v[94:97], v18 offset:17088
	s_waitcnt lgkmcnt(0)
	v_mfma_f32_16x16x32_bf16 v[56:59], v[94:97], v[200:203], v[56:59]
	v_mfma_f32_16x16x32_bf16 v[60:63], v[94:97], v[204:207], v[60:63]
	v_mfma_f32_16x16x32_bf16 v[64:67], v[94:97], v[208:211], v[64:67]
	v_mfma_f32_16x16x32_bf16 v[52:55], v[94:97], v[212:215], v[52:55]
	ds_read_b128 v[94:97], v18 offset:25536
	s_waitcnt lgkmcnt(0)
	v_mfma_f32_16x16x32_bf16 v[4:7], v[94:97], v[200:203], v[4:7]
	v_mfma_f32_16x16x32_bf16 v[8:11], v[94:97], v[204:207], v[8:11]
	v_mfma_f32_16x16x32_bf16 v[12:15], v[94:97], v[208:211], v[12:15]
	v_mfma_f32_16x16x32_bf16 v[0:3], v[94:97], v[212:215], v[0:3]
	ds_read_b128 v[94:97], v18 offset:256
	v_add_co_u32_e32 v88, vcc, s0, v16
	s_waitcnt lgkmcnt(0)
	v_mfma_f32_16x16x32_bf16 v[20:23], v[94:97], v[216:219], v[20:23]
	v_addc_co_u32_e32 v89, vcc, 0, v17, vcc
	s_mov_b32 s0, 0x30000
	v_mfma_f32_16x16x32_bf16 v[24:27], v[94:97], v[220:223], v[24:27]
	v_mfma_f32_16x16x32_bf16 v[28:31], v[94:97], v[224:227], v[28:31]
	v_mfma_f32_16x16x32_bf16 v[32:35], v[94:97], v[228:231], v[32:35]
	ds_read_b128 v[94:97], v18 offset:8704
	s_waitcnt lgkmcnt(0)
	v_mfma_f32_16x16x32_bf16 v[40:43], v[94:97], v[216:219], v[40:43]
	v_mfma_f32_16x16x32_bf16 v[44:47], v[94:97], v[220:223], v[44:47]
	v_mfma_f32_16x16x32_bf16 v[48:51], v[94:97], v[224:227], v[48:51]
	v_mfma_f32_16x16x32_bf16 v[36:39], v[94:97], v[228:231], v[36:39]
	ds_read_b128 v[94:97], v18 offset:17152
	s_waitcnt lgkmcnt(0)
	v_mfma_f32_16x16x32_bf16 v[56:59], v[94:97], v[216:219], v[56:59]
	v_mfma_f32_16x16x32_bf16 v[60:63], v[94:97], v[220:223], v[60:63]
	v_mfma_f32_16x16x32_bf16 v[64:67], v[94:97], v[224:227], v[64:67]
	v_mfma_f32_16x16x32_bf16 v[52:55], v[94:97], v[228:231], v[52:55]
	ds_read_b128 v[94:97], v18 offset:25600
	s_waitcnt lgkmcnt(0)
	v_mfma_f32_16x16x32_bf16 v[4:7], v[94:97], v[216:219], v[4:7]
	v_mfma_f32_16x16x32_bf16 v[8:11], v[94:97], v[220:223], v[8:11]
	v_mfma_f32_16x16x32_bf16 v[12:15], v[94:97], v[224:227], v[12:15]
	v_mfma_f32_16x16x32_bf16 v[0:3], v[94:97], v[228:231], v[0:3]
	ds_read_b128 v[94:97], v18 offset:320
	v_add_co_u32_e32 v88, vcc, s0, v16
	s_waitcnt lgkmcnt(0)
	v_mfma_f32_16x16x32_bf16 v[20:23], v[94:97], v[232:235], v[20:23]
	v_addc_co_u32_e32 v89, vcc, 0, v17, vcc
	s_mov_b32 s0, 0x38000
	v_mfma_f32_16x16x32_bf16 v[24:27], v[94:97], v[238:241], v[24:27]
	v_add_co_u32_e32 v16, vcc, s0, v16
	s_lshl_b64 s[0:1], s[6:7], 9
	v_mfma_f32_16x16x32_bf16 v[28:31], v[94:97], v[242:245], v[28:31]
	v_addc_co_u32_e32 v17, vcc, 0, v17, vcc
	v_mfma_f32_16x16x32_bf16 v[32:35], v[94:97], v[246:249], v[32:35]
	ds_read_b128 v[94:97], v18 offset:8768
	s_waitcnt lgkmcnt(0)
	v_mfma_f32_16x16x32_bf16 v[40:43], v[94:97], v[232:235], v[40:43]
	v_mfma_f32_16x16x32_bf16 v[44:47], v[94:97], v[238:241], v[44:47]
	v_mfma_f32_16x16x32_bf16 v[48:51], v[94:97], v[242:245], v[48:51]
	v_mfma_f32_16x16x32_bf16 v[36:39], v[94:97], v[246:249], v[36:39]
	ds_read_b128 v[94:97], v18 offset:17216
	s_waitcnt lgkmcnt(0)
	v_mfma_f32_16x16x32_bf16 v[56:59], v[94:97], v[232:235], v[56:59]
	v_mfma_f32_16x16x32_bf16 v[60:63], v[94:97], v[238:241], v[60:63]
	v_mfma_f32_16x16x32_bf16 v[64:67], v[94:97], v[242:245], v[64:67]
	v_mfma_f32_16x16x32_bf16 v[52:55], v[94:97], v[246:249], v[52:55]
	ds_read_b128 v[94:97], v18 offset:25664
	s_waitcnt lgkmcnt(0)
	v_mfma_f32_16x16x32_bf16 v[4:7], v[94:97], v[232:235], v[4:7]
	v_mfma_f32_16x16x32_bf16 v[8:11], v[94:97], v[238:241], v[8:11]
	v_mfma_f32_16x16x32_bf16 v[12:15], v[94:97], v[242:245], v[12:15]
	v_mfma_f32_16x16x32_bf16 v[0:3], v[94:97], v[246:249], v[0:3]
	ds_read_b128 v[94:97], v18 offset:384
	s_waitcnt lgkmcnt(0)
	s_waitcnt vmcnt(7)
	v_mfma_f32_16x16x32_bf16 v[20:23], v[94:97], v[142:145], v[20:23]
	s_waitcnt vmcnt(6)
	v_mfma_f32_16x16x32_bf16 v[24:27], v[94:97], v[146:149], v[24:27]
	s_waitcnt vmcnt(5)
	v_mfma_f32_16x16x32_bf16 v[28:31], v[94:97], v[150:153], v[28:31]
	s_waitcnt vmcnt(4)
; #define LAS __attribute__((address_space(3)))
; __device__ __forceinline__ void gla_out_unit(const Params& P, LAS unsigned char* lds, int u) {
;     ...
;     for (int kb = 0; kb < 10; ++kb) { bf16x8 bfr[4], afr[4];
; #pragma unroll
;         for (int j = 0; j < 4; ++j) bfr[j] = kb < 8 ? __builtin_nontemporal_load((const bf16x8*)(stp + (size_t)(2 * kb) * 8192 + 16 * j * 16)) : *(const bf16x8*)(vtp + (size_t)(16 * j) * 64 + 32 * (kb - 8));
; #pragma unroll
;         for (int m = 0; m < 4; ++m) afr[m] = kb < 8 ? *(const LAS bf16x8*)(QS + (16 * m + fr) * 264 + 32 * kb + 8 * q4) : *(const LAS bf16x8*)(AS + (16 * m + fr) * 72 + 32 * (kb - 8) + 8 * q4);
; #pragma unroll
;         for (int m = 0; m < 4; ++m)
; #pragma unroll
;             for (int j = 0; j < 4; ++j) acc[m][j] = __builtin_amdgcn_mfma_f32_16x16x32_bf16(afr[m], bfr[j], acc[m][j], 0, 0, 0); }
; #pragma unroll
;     for (int m = 0; m < 4; ++m)
; #pragma unroll
;         for (int i = 0; i < 4; ++i) { float s = 0.f;
; #pragma unroll
;             for (int j = 0; j < 4; ++j) s += acc[m][j][i] * acc[m][j][i];
;             s += __shfl_xor(s, 1); s += __shfl_xor(s, 2); s += __shfl_xor(s, 4); s += __shfl_xor(s, 8);
;             if (fr == 0) SS[wave * 64 + 16 * m + 4 * q4 + i] = s; }
	v_mfma_f32_16x16x32_bf16 v[32:35], v[94:97], v[154:157], v[32:35]
	ds_read_b128 v[94:97], v18 offset:8832
	s_waitcnt lgkmcnt(0)
	v_mfma_f32_16x16x32_bf16 v[40:43], v[94:97], v[142:145], v[40:43]
	v_mfma_f32_16x16x32_bf16 v[44:47], v[94:97], v[146:149], v[44:47]
	v_mfma_f32_16x16x32_bf16 v[48:51], v[94:97], v[150:153], v[48:51]
	v_mfma_f32_16x16x32_bf16 v[36:39], v[94:97], v[154:157], v[36:39]
	ds_read_b128 v[94:97], v18 offset:17280
	s_waitcnt lgkmcnt(0)
	v_mfma_f32_16x16x32_bf16 v[56:59], v[94:97], v[142:145], v[56:59]
	v_mfma_f32_16x16x32_bf16 v[60:63], v[94:97], v[146:149], v[60:63]
	v_mfma_f32_16x16x32_bf16 v[64:67], v[94:97], v[150:153], v[64:67]
	v_mfma_f32_16x16x32_bf16 v[52:55], v[94:97], v[154:157], v[52:55]
	ds_read_b128 v[94:97], v18 offset:25728
	s_waitcnt lgkmcnt(0)
	v_mfma_f32_16x16x32_bf16 v[98:101], v[94:97], v[142:145], v[4:7]
	v_mfma_f32_16x16x32_bf16 v[8:11], v[94:97], v[146:149], v[8:11]
	v_mfma_f32_16x16x32_bf16 v[4:7], v[94:97], v[150:153], v[12:15]
	s_nop 1
	v_mfma_f32_16x16x32_bf16 v[0:3], v[94:97], v[154:157], v[0:3]
	ds_read_b128 v[94:97], v18 offset:448
	v_lshl_add_u64 v[16:17], s[0:1], 0, v[72:73]
	s_waitcnt lgkmcnt(0)
	s_waitcnt vmcnt(3)
	v_mfma_f32_16x16x32_bf16 v[20:23], v[94:97], v[158:161], v[20:23]
	v_or_b32_e32 v16, v16, v91
	v_lshlrev_b64 v[16:17], 7, v[16:17]
	v_lshl_add_u64 v[16:17], s[90:91], 0, v[16:17]
	s_waitcnt vmcnt(2)
	v_mfma_f32_16x16x32_bf16 v[24:27], v[94:97], v[162:165], v[24:27]
	v_lshl_add_u64 v[16:17], v[16:17], 0, v[68:69]
	s_mov_b32 s0, 0x17401000
	v_add_co_u32_e32 v88, vcc, s0, v16
	s_waitcnt vmcnt(1)
	v_mfma_f32_16x16x32_bf16 v[28:31], v[94:97], v[166:169], v[28:31]
	s_nop 0
	v_addc_co_u32_e32 v89, vcc, 0, v17, vcc
	s_mov_b32 s0, 0x17400000
	s_waitcnt vmcnt(0)
	v_mfma_f32_16x16x32_bf16 v[32:35], v[94:97], v[180:183], v[32:35]
	ds_read_b128 v[94:97], v18 offset:8896
	v_add_co_u32_e32 v126, vcc, s0, v16
	s_waitcnt lgkmcnt(0)
	v_mfma_f32_16x16x32_bf16 v[40:43], v[94:97], v[158:161], v[40:43]
	v_addc_co_u32_e32 v127, vcc, 0, v17, vcc
	v_mad_i32_i24 v68, v91, s22, v18
	v_mfma_f32_16x16x32_bf16 v[44:47], v[94:97], v[162:165], v[44:47]
	v_cmp_lt_i32_e32 vcc, v176, v177
	v_mfma_f32_16x16x32_bf16 v[48:51], v[94:97], v[166:169], v[48:51]
	v_mfma_f32_16x16x32_bf16 v[36:39], v[94:97], v[180:183], v[36:39]
	ds_read_b128 v[94:97], v18 offset:17344
	s_waitcnt lgkmcnt(0)
	v_mfma_f32_16x16x32_bf16 v[56:59], v[94:97], v[158:161], v[56:59]
	v_mfma_f32_16x16x32_bf16 v[60:63], v[94:97], v[162:165], v[60:63]
	v_mfma_f32_16x16x32_bf16 v[64:67], v[94:97], v[166:169], v[64:67]
	v_mfma_f32_16x16x32_bf16 v[52:55], v[94:97], v[180:183], v[52:55]
	global_load_dwordx4 v[94:97], v[88:89], off offset:-4096
	v_mfma_f32_16x16x32_bf16 v[12:15], v[114:117], v[158:161], v[98:101]
	v_mfma_f32_16x16x32_bf16 v[8:11], v[114:117], v[162:165], v[8:11]
	global_load_dwordx4 v[102:105], v[126:127], off offset:2048
	v_mfma_f32_16x16x32_bf16 v[98:101], v[114:117], v[166:169], v[4:7]
	global_load_dwordx4 v[106:109], v[88:89], off
	v_mfma_f32_16x16x32_bf16 v[0:3], v[114:117], v[180:183], v[0:3]
	global_load_dwordx4 v[114:117], v[88:89], off offset:2048
	ds_read_b128 v[4:7], v68 offset:33792
	s_waitcnt lgkmcnt(0)
	s_waitcnt vmcnt(3)
	v_mfma_f32_16x16x32_bf16 v[20:23], v[4:7], v[94:97], v[20:23]
	s_waitcnt vmcnt(2)
	v_mfma_f32_16x16x32_bf16 v[24:27], v[4:7], v[102:105], v[24:27]
	s_waitcnt vmcnt(1)
	v_mfma_f32_16x16x32_bf16 v[110:113], v[4:7], v[106:109], v[28:31]
	s_waitcnt vmcnt(0)
	v_mfma_f32_16x16x32_bf16 v[32:35], v[4:7], v[114:117], v[32:35]
	ds_read_b128 v[4:7], v68 offset:36096
	s_waitcnt lgkmcnt(0)
	v_mfma_f32_16x16x32_bf16 v[40:43], v[4:7], v[94:97], v[40:43]
	v_mfma_f32_16x16x32_bf16 v[118:121], v[4:7], v[102:105], v[44:47]
	v_mfma_f32_16x16x32_bf16 v[122:125], v[4:7], v[106:109], v[48:51]
	v_mfma_f32_16x16x32_bf16 v[130:133], v[4:7], v[114:117], v[36:39]
	ds_read_b128 v[4:7], v68 offset:38400
	s_nop 1
	ds_read_b128 v[36:39], v68 offset:40704
	s_waitcnt lgkmcnt(1)
	v_mfma_f32_16x16x32_bf16 v[28:31], v[4:7], v[106:109], v[64:67]
	s_nop 2
	global_load_dwordx4 v[64:67], v[126:127], off offset:64
	v_mfma_f32_16x16x32_bf16 v[134:137], v[4:7], v[94:97], v[56:59]
	s_waitcnt lgkmcnt(0)
	v_mfma_f32_16x16x32_bf16 v[12:15], v[36:39], v[94:97], v[12:15]
	global_load_dwordx4 v[94:97], v[126:127], off offset:2112
	v_mfma_f32_16x16x32_bf16 v[138:141], v[4:7], v[102:105], v[60:63]
	v_mfma_f32_16x16x32_bf16 v[16:19], v[4:7], v[114:117], v[52:55]
	v_mfma_f32_16x16x32_bf16 v[4:7], v[36:39], v[102:105], v[8:11]
	global_load_dwordx4 v[102:105], v[88:89], off offset:2112
	v_mfma_f32_16x16x32_bf16 v[8:11], v[36:39], v[106:109], v[98:101]
	s_nop 2
	global_load_dwordx4 v[98:101], v[88:89], off offset:64
	v_mfma_f32_16x16x32_bf16 v[0:3], v[36:39], v[114:117], v[0:3]
	ds_read_b128 v[36:39], v68 offset:33856
	s_waitcnt lgkmcnt(0)
	s_waitcnt vmcnt(3)
	v_mfma_f32_16x16x32_bf16 v[56:59], v[36:39], v[64:67], v[20:23]
	s_nop 2
	ds_read_b128 v[20:23], v68 offset:36160
	s_waitcnt vmcnt(2)
	v_mfma_f32_16x16x32_bf16 v[52:55], v[36:39], v[94:97], v[24:27]
	s_waitcnt vmcnt(0)
	v_mfma_f32_16x16x32_bf16 v[60:63], v[36:39], v[98:101], v[110:113]
	s_nop 5
	v_mul_f32_e32 v88, v52, v52
	v_fmac_f32_e32 v88, v56, v56
	ds_read_b128 v[106:109], v68 offset:38464
	ds_read_b128 v[110:113], v68 offset:40768
	v_mfma_f32_16x16x32_bf16 v[48:51], v[36:39], v[102:105], v[32:35]
	v_fmac_f32_e32 v88, v60, v60
	s_waitcnt lgkmcnt(2)
	v_mfma_f32_16x16x32_bf16 v[44:47], v[20:23], v[64:67], v[40:43]
	v_mfma_f32_16x16x32_bf16 v[40:43], v[20:23], v[94:97], v[118:121]
	s_nop 3
	v_fmac_f32_e32 v88, v48, v48
	v_mfma_f32_16x16x32_bf16 v[36:39], v[20:23], v[98:101], v[122:125]
	v_mfma_f32_16x16x32_bf16 v[32:35], v[20:23], v[102:105], v[130:133]
	v_cndmask_b32_e32 v20, v175, v176, vcc
	v_lshlrev_b32_e32 v68, 2, v20
	ds_bpermute_b32 v89, v68, v88
	v_cmp_lt_i32_e32 vcc, v74, v177
	s_waitcnt lgkmcnt(2)
	v_mfma_f32_16x16x32_bf16 v[20:23], v[106:109], v[64:67], v[134:137]
	s_waitcnt lgkmcnt(0)
	v_add_f32_e32 v88, v88, v89
	v_cndmask_b32_e32 v73, v175, v74, vcc
	v_lshlrev_b32_e32 v73, 2, v73
	ds_bpermute_b32 v89, v73, v88
	v_cmp_lt_i32_e32 vcc, v75, v177
	v_mfma_f32_16x16x32_bf16 v[12:15], v[110:113], v[64:67], v[12:15]
	s_waitcnt lgkmcnt(0)
	v_add_f32_e32 v67, v88, v89
	v_cndmask_b32_e32 v90, v175, v75, vcc
	v_lshlrev_b32_e32 v64, 2, v90
	ds_bpermute_b32 v88, v64, v67
	v_cmp_lt_i32_e32 vcc, v76, v177
	v_mfma_f32_16x16x32_bf16 v[24:27], v[106:109], v[94:97], v[138:141]
	s_waitcnt lgkmcnt(0)
	v_add_f32_e32 v67, v67, v88
	v_cndmask_b32_e32 v65, v175, v76, vcc
	v_lshlrev_b32_e32 v66, 2, v65
	ds_bpermute_b32 v88, v66, v67
	v_mfma_f32_16x16x32_bf16 v[28:31], v[106:109], v[98:101], v[28:31]
	v_cmp_eq_u32_e32 vcc, 0, v91
	v_lshl_add_u32 v65, v72, 2, v87
	v_mfma_f32_16x16x32_bf16 v[16:19], v[106:109], v[102:105], v[16:19]
	v_mfma_f32_16x16x32_bf16 v[4:7], v[110:113], v[94:97], v[4:7]
	v_mfma_f32_16x16x32_bf16 v[8:11], v[110:113], v[98:101], v[8:11]
	v_mfma_f32_16x16x32_bf16 v[0:3], v[110:113], v[102:105], v[0:3]
	s_and_saveexec_b64 s[0:1], vcc
	s_cbranch_execz .LBB0_487
; __device__ __forceinline__ void gla_out_unit(const Params& P, LAS unsigned char* lds, int u) {
;     ...
;             if (fr == 0) SS[wave * 64 + 16 * m + 4 * q4 + i] = s; }
	s_waitcnt lgkmcnt(0)
	v_add_f32_e32 v67, v67, v88
	ds_write_b32 v65, v67 offset:43008
